# GEMM K-loops (6 phases): next-tile operands loaded HBM->LDS directly (global_load_lds_dwordx4, swizzle on the source column, m0 = stage base); no staging VGPRs, ds_writes, vmcnt ladder or per-iteratio
# speedup vs baseline: 1.0086x; 1.0074x over previous
.LBB0_248:
	s_lshl_b32 s56, s52, 8
	v_or_b32_e32 v2, s56, v1
	v_ashrrev_i32_e32 v3, 31, v2
	v_lshlrev_b64 v[62:63], 11, v[2:3]
	v_lshl_add_u64 v[2:3], v[130:131], 0, v[62:63]
	v_add_co_u32_e32 v6, vcc, 0x20000, v2
	s_lshl_b32 s53, s47, 8
	s_nop 0
	v_addc_co_u32_e32 v7, vcc, 0, v3, vcc
	v_or_b32_e32 v4, s53, v1
	global_load_dwordx4 v[30:33], v[2:3], off
	global_load_dwordx4 v[34:37], v[6:7], off
	v_add_co_u32_e32 v6, vcc, 0x40000, v2
	v_ashrrev_i32_e32 v5, 31, v4
	s_nop 0
	v_addc_co_u32_e32 v7, vcc, 0, v3, vcc
	v_lshlrev_b64 v[64:65], 11, v[4:5]
	v_add_co_u32_e32 v2, vcc, 0x60000, v2
	v_lshl_add_u64 v[4:5], v[132:133], 0, v[64:65]
	s_nop 0
	v_addc_co_u32_e32 v3, vcc, 0, v3, vcc
	global_load_dwordx4 v[38:41], v[6:7], off
	global_load_dwordx4 v[42:45], v[2:3], off
	v_add_co_u32_e32 v2, vcc, s12, v4
	s_waitcnt vmcnt(63) expcnt(7) lgkmcnt(15)
	s_nop 0
	v_addc_co_u32_e32 v3, vcc, 0, v5, vcc
	s_barrier
	global_load_dwordx4 v[46:49], v[4:5], off
	global_load_dwordx4 v[50:53], v[2:3], off
	v_add_co_u32_e32 v2, vcc, s13, v4
	s_mov_b32 s57, 0
	s_nop 0
	v_addc_co_u32_e32 v3, vcc, 0, v5, vcc
	v_add_co_u32_e32 v4, vcc, s14, v4
	s_mov_b64 s[8:9], 0
	s_nop 0
	v_addc_co_u32_e32 v5, vcc, 0, v5, vcc
	global_load_dwordx4 v[54:57], v[2:3], off
	global_load_dwordx4 v[58:61], v[4:5], off
	v_mov_b32_e32 v2, 0
	v_mov_b32_e32 v3, v2
	v_mov_b32_e32 v4, v2
	v_mov_b32_e32 v5, v2
	v_mov_b32_e32 v6, v2
	v_mov_b32_e32 v7, v2
	v_mov_b32_e32 v8, v2
	v_mov_b32_e32 v9, v2
	v_mov_b32_e32 v10, v2
	v_mov_b32_e32 v11, v2
	v_mov_b32_e32 v12, v2
	v_mov_b32_e32 v13, v2
	v_mov_b32_e32 v14, v2
	v_mov_b32_e32 v15, v2
	v_mov_b32_e32 v16, v2
	v_mov_b32_e32 v17, v2
	v_mov_b32_e32 v18, v2
	v_mov_b32_e32 v19, v2
	v_mov_b32_e32 v20, v2
	v_mov_b32_e32 v21, v2
	v_mov_b32_e32 v22, v2
	v_mov_b32_e32 v23, v2
	v_mov_b32_e32 v24, v2
	v_mov_b32_e32 v25, v2
	v_mov_b32_e32 v26, v2
	v_mov_b32_e32 v27, v2
	v_mov_b32_e32 v28, v2
	v_lshl_add_u64 v[136:137], v[134:135], 0, v[62:63]
	v_lshl_add_u64 v[138:139], v[134:135], 0, v[64:65]
	v_mov_b32_e32 v29, v2
	v_mov_b32_e32 v62, v2
	v_mov_b32_e32 v63, v2
	v_mov_b32_e32 v64, v2
	v_mov_b32_e32 v65, v2
	v_mov_b32_e32 v66, v2
	v_mov_b32_e32 v67, v2
	v_mov_b32_e32 v68, v2
	v_mov_b32_e32 v69, v2
	v_mov_b32_e32 v70, v2
	v_mov_b32_e32 v71, v2
	v_mov_b32_e32 v72, v2
	v_mov_b32_e32 v73, v2
	v_mov_b32_e32 v74, v2
	v_mov_b32_e32 v75, v2
	v_mov_b32_e32 v76, v2
	v_mov_b32_e32 v77, v2
	v_mov_b32_e32 v78, v2
	v_mov_b32_e32 v79, v2
	v_mov_b32_e32 v80, v2
	v_mov_b32_e32 v81, v2
	v_mov_b32_e32 v82, v2
	v_mov_b32_e32 v83, v2
	v_mov_b32_e32 v84, v2
	s_waitcnt vmcnt(7)
	ds_write_b128 v146, v[30:33]
	s_waitcnt vmcnt(6)
	ds_write_b128 v146, v[34:37] offset:8192
	s_waitcnt vmcnt(5)
	ds_write_b128 v146, v[38:41] offset:16384
	s_waitcnt vmcnt(4)
	ds_write_b128 v146, v[42:45] offset:24576
	s_waitcnt vmcnt(3)
	ds_write_b128 v147, v[46:49]
	s_waitcnt vmcnt(2)
	ds_write_b128 v147, v[50:53] offset:8192
	s_waitcnt vmcnt(1)
	ds_write_b128 v147, v[54:57] offset:16384
	s_waitcnt vmcnt(0)
	ds_write_b128 v147, v[58:61] offset:24576
	v_mov_b32_e32 v30, v2
	v_mov_b32_e32 v31, v2
	v_mov_b32_e32 v32, v2
	v_mov_b32_e32 v33, v2
	v_mov_b32_e32 v34, v2
	v_mov_b32_e32 v35, v2
	v_mov_b32_e32 v36, v2
	v_mov_b32_e32 v37, v2
	v_mov_b32_e32 v38, v2
	v_mov_b32_e32 v39, v2
	v_mov_b32_e32 v40, v2
	v_mov_b32_e32 v41, v2
	v_mov_b32_e32 v42, v2
	v_mov_b32_e32 v43, v2
	v_mov_b32_e32 v44, v2
	v_mov_b32_e32 v45, v2
	v_mov_b32_e32 v46, v2
	v_mov_b32_e32 v47, v2
	v_mov_b32_e32 v48, v2
	v_mov_b32_e32 v49, v2
	v_mov_b32_e32 v50, v2
	v_mov_b32_e32 v51, v2
	v_mov_b32_e32 v52, v2
	v_mov_b32_e32 v53, v2
	v_mov_b32_e32 v54, v2
	v_mov_b32_e32 v55, v2
	v_mov_b32_e32 v56, v2
	v_mov_b32_e32 v57, v2
	v_mov_b32_e32 v58, v2
	v_mov_b32_e32 v59, v2
	v_mov_b32_e32 v60, v2
	v_mov_b32_e32 v61, v2
	v_mov_b32_e32 v85, v2
	v_mov_b32_e32 v86, v2
	v_mov_b32_e32 v87, v2
	v_mov_b32_e32 v88, v2
	v_mov_b32_e32 v89, v2
	v_mov_b32_e32 v90, v2
	v_mov_b32_e32 v91, v2
	v_mov_b32_e32 v92, v2
	v_mov_b32_e32 v93, v2
	v_mov_b32_e32 v94, v2
	v_mov_b32_e32 v95, v2
	v_mov_b32_e32 v96, v2
	v_mov_b32_e32 v97, v2
	v_mov_b32_e32 v98, v2
	v_mov_b32_e32 v99, v2
	v_mov_b32_e32 v100, v2
	v_mov_b32_e32 v101, v2
	v_mov_b32_e32 v102, v2
	v_mov_b32_e32 v103, v2
	v_mov_b32_e32 v104, v2
	v_mov_b32_e32 v105, v2
	v_mov_b32_e32 v106, v2
	v_mov_b32_e32 v107, v2
	v_mov_b32_e32 v108, v2
	v_mov_b32_e32 v109, v2
	v_mov_b32_e32 v110, v2
	v_mov_b32_e32 v111, v2
	v_mov_b32_e32 v112, v2
	v_mov_b32_e32 v113, v2
	v_mov_b32_e32 v114, v2
	v_mov_b32_e32 v115, v2
	v_mov_b32_e32 v116, v2
	v_mov_b32_e32 v117, v2
	v_mov_b32_e32 v118, v2
	v_mov_b32_e32 v119, v2
	v_mov_b32_e32 v120, v2
	v_mov_b32_e32 v121, v2
	v_mov_b32_e32 v122, v2
	v_mov_b32_e32 v123, v2
	v_mov_b32_e32 v124, v2
	v_mov_b32_e32 v125, v2
	v_mov_b32_e32 v126, v2
	v_mov_b32_e32 v127, v2
	v_mov_b32_e32 v128, v2
	v_mov_b32_e32 v129, v2
	s_waitcnt lgkmcnt(0)
	s_barrier
	s_movk_i32 s97, 0x70
	v_readfirstlane_b32 s98, v136
	v_readfirstlane_b32 s99, v137
	v_subrev_u32_e32 v248, s98, v136
	v_bfi_b32 v248, s97, v146, v248
	v_add_u32_e32 v140, s15, v248
	v_add_u32_e32 v152, s16, v248
	v_add_u32_e32 v156, s17, v248
	v_add_u32_e32 v160, s28, v248
	s_add_u32 s98, s98, s8
	s_addc_u32 s99, s99, s9
	s_add_u32 s98, s98, 0x80
	s_addc_u32 s99, s99, 0
	v_readfirstlane_b32 s100, v138
	v_readfirstlane_b32 s101, v139
	v_subrev_u32_e32 v250, s100, v138
	v_bfi_b32 v250, s97, v146, v250
	v_add_u32_e32 v164, s29, v250
	v_add_u32_e32 v168, s38, v250
	v_add_u32_e32 v172, s39, v250
	v_add_u32_e32 v176, s42, v250
	s_add_u32 s100, s100, s8
	s_addc_u32 s101, s101, s9
	s_add_u32 s100, s100, 0x80
	s_addc_u32 s101, s101, 0
	v_readfirstlane_b32 s96, v146
	s_and_b32 s96, s96, 0xfc00
	s_xor_b32 s96, s96, 0x8000
	s_mov_b32 m0, s96
	s_nop 0
	global_load_lds_dwordx4 v140, s[98:99]
	s_add_u32 m0, m0, 0x2000
	s_nop 0
	global_load_lds_dwordx4 v152, s[98:99]
	s_add_u32 m0, m0, 0x2000
	s_nop 0
	global_load_lds_dwordx4 v156, s[98:99]
	s_add_u32 m0, m0, 0x2000
	s_nop 0
	global_load_lds_dwordx4 v160, s[98:99]
	s_add_u32 m0, m0, 0xa000
	s_nop 0
	global_load_lds_dwordx4 v164, s[100:101]
	s_add_u32 m0, m0, 0x2000
	s_nop 0
	global_load_lds_dwordx4 v168, s[100:101]
	s_add_u32 m0, m0, 0x2000
	s_nop 0
	global_load_lds_dwordx4 v172, s[100:101]
	s_add_u32 m0, m0, 0x2000
	s_nop 0
	global_load_lds_dwordx4 v176, s[100:101]
	v_mov_b32_e32 v223, v148
	v_mov_b32_e32 v249, v149
	ds_read_b128 v[180:183], v223
	ds_read_b128 v[184:187], v223 offset:2048
	ds_read_b128 v[188:191], v223 offset:4096
	ds_read_b128 v[192:195], v223 offset:6144
	ds_read_b128 v[212:215], v249
	ds_read_b128 v[218:221], v249 offset:2048
	ds_read_b128 v[224:227], v249 offset:4096
	ds_read_b128 v[228:231], v249 offset:6144
.Lg2_p4_loop:
	ds_read_b128 v[196:199], v223 offset:8192
	ds_read_b128 v[200:203], v223 offset:10240
	ds_read_b128 v[204:207], v223 offset:12288
	ds_read_b128 v[208:211], v223 offset:14336
	s_waitcnt lgkmcnt(4)
	v_mfma_f32_16x16x32_bf16 v[126:129], v[212:215], v[180:183], v[126:129]
	v_mfma_f32_16x16x32_bf16 v[122:125], v[218:221], v[180:183], v[122:125]
	v_mfma_f32_16x16x32_bf16 v[118:121], v[224:227], v[180:183], v[118:121]
	v_mfma_f32_16x16x32_bf16 v[114:117], v[228:231], v[180:183], v[114:117]
	v_mfma_f32_16x16x32_bf16 v[110:113], v[212:215], v[184:187], v[110:113]
	v_mfma_f32_16x16x32_bf16 v[106:109], v[218:221], v[184:187], v[106:109]
	v_mfma_f32_16x16x32_bf16 v[102:105], v[224:227], v[184:187], v[102:105]
	v_mfma_f32_16x16x32_bf16 v[98:101], v[228:231], v[184:187], v[98:101]
	v_mfma_f32_16x16x32_bf16 v[94:97], v[212:215], v[188:191], v[94:97]
	v_mfma_f32_16x16x32_bf16 v[90:93], v[218:221], v[188:191], v[90:93]
	v_mfma_f32_16x16x32_bf16 v[86:89], v[224:227], v[188:191], v[86:89]
	v_mfma_f32_16x16x32_bf16 v[82:85], v[228:231], v[188:191], v[82:85]
	v_mfma_f32_16x16x32_bf16 v[78:81], v[212:215], v[192:195], v[78:81]
	v_mfma_f32_16x16x32_bf16 v[74:77], v[218:221], v[192:195], v[74:77]
	v_mfma_f32_16x16x32_bf16 v[70:73], v[224:227], v[192:195], v[70:73]
	v_mfma_f32_16x16x32_bf16 v[66:69], v[228:231], v[192:195], v[66:69]
	ds_read_b128 v[180:183], v216
	ds_read_b128 v[184:187], v216 offset:2048
	ds_read_b128 v[188:191], v216 offset:4096
	ds_read_b128 v[192:195], v216 offset:6144
	ds_read_b128 v[232:235], v217
	ds_read_b128 v[236:239], v217 offset:2048
	ds_read_b128 v[240:243], v217 offset:4096
	ds_read_b128 v[244:247], v217 offset:6144
	s_waitcnt lgkmcnt(8)
	v_mfma_f32_16x16x32_bf16 v[62:65], v[212:215], v[196:199], v[62:65]
	v_mfma_f32_16x16x32_bf16 v[58:61], v[218:221], v[196:199], v[58:61]
	v_mfma_f32_16x16x32_bf16 v[54:57], v[224:227], v[196:199], v[54:57]
	v_mfma_f32_16x16x32_bf16 v[50:53], v[228:231], v[196:199], v[50:53]
	v_mfma_f32_16x16x32_bf16 v[46:49], v[212:215], v[200:203], v[46:49]
	v_mfma_f32_16x16x32_bf16 v[42:45], v[218:221], v[200:203], v[42:45]
	v_mfma_f32_16x16x32_bf16 v[38:41], v[224:227], v[200:203], v[38:41]
	v_mfma_f32_16x16x32_bf16 v[34:37], v[228:231], v[200:203], v[34:37]
	v_mfma_f32_16x16x32_bf16 v[30:33], v[212:215], v[204:207], v[30:33]
	v_mfma_f32_16x16x32_bf16 v[26:29], v[218:221], v[204:207], v[26:29]
	v_mfma_f32_16x16x32_bf16 v[22:25], v[224:227], v[204:207], v[22:25]
	v_mfma_f32_16x16x32_bf16 v[18:21], v[228:231], v[204:207], v[18:21]
	v_mfma_f32_16x16x32_bf16 v[14:17], v[212:215], v[208:211], v[14:17]
	v_mfma_f32_16x16x32_bf16 v[10:13], v[218:221], v[208:211], v[10:13]
	v_mfma_f32_16x16x32_bf16 v[6:9], v[224:227], v[208:211], v[6:9]
	v_mfma_f32_16x16x32_bf16 v[2:5], v[228:231], v[208:211], v[2:5]
	ds_read_b128 v[196:199], v216 offset:8192
	ds_read_b128 v[200:203], v216 offset:10240
	ds_read_b128 v[204:207], v216 offset:12288
	ds_read_b128 v[208:211], v216 offset:14336
	s_waitcnt lgkmcnt(4)
	v_mfma_f32_16x16x32_bf16 v[126:129], v[232:235], v[180:183], v[126:129]
	v_mfma_f32_16x16x32_bf16 v[122:125], v[236:239], v[180:183], v[122:125]
	v_mfma_f32_16x16x32_bf16 v[118:121], v[240:243], v[180:183], v[118:121]
	v_mfma_f32_16x16x32_bf16 v[114:117], v[244:247], v[180:183], v[114:117]
	v_mfma_f32_16x16x32_bf16 v[110:113], v[232:235], v[184:187], v[110:113]
	v_mfma_f32_16x16x32_bf16 v[106:109], v[236:239], v[184:187], v[106:109]
	v_mfma_f32_16x16x32_bf16 v[102:105], v[240:243], v[184:187], v[102:105]
	v_mfma_f32_16x16x32_bf16 v[98:101], v[244:247], v[184:187], v[98:101]
	v_mfma_f32_16x16x32_bf16 v[94:97], v[232:235], v[188:191], v[94:97]
	v_mfma_f32_16x16x32_bf16 v[90:93], v[236:239], v[188:191], v[90:93]
	v_mfma_f32_16x16x32_bf16 v[86:89], v[240:243], v[188:191], v[86:89]
	v_mfma_f32_16x16x32_bf16 v[82:85], v[244:247], v[188:191], v[82:85]
	v_mfma_f32_16x16x32_bf16 v[78:81], v[232:235], v[192:195], v[78:81]
	v_mfma_f32_16x16x32_bf16 v[74:77], v[236:239], v[192:195], v[74:77]
	v_mfma_f32_16x16x32_bf16 v[70:73], v[240:243], v[192:195], v[70:73]
	v_mfma_f32_16x16x32_bf16 v[66:69], v[244:247], v[192:195], v[66:69]
	s_waitcnt vmcnt(0)
	s_waitcnt lgkmcnt(0)
	s_barrier
	s_add_u32 s8, s8, 0x80
	s_addc_u32 s9, s9, 0
	s_add_u32 s98, s98, 0x80
	s_addc_u32 s99, s99, 0
	s_add_u32 s100, s100, 0x80
	s_addc_u32 s101, s101, 0
	s_cmpk_eq_i32 s8, 0x780
	s_cbranch_scc1 .Lg2_p4_tail
	v_xor_b32_e32 v223, 0x8000, v223
	v_xor_b32_e32 v249, 0x8000, v249
	v_xor_b32_e32 v216, 0x8000, v216
	v_xor_b32_e32 v217, 0x8000, v217
	s_xor_b32 s96, s96, 0x8000
	ds_read_b128 v[180:183], v223
	ds_read_b128 v[184:187], v223 offset:2048
	ds_read_b128 v[188:191], v223 offset:4096
	ds_read_b128 v[192:195], v223 offset:6144
	ds_read_b128 v[212:215], v249
	ds_read_b128 v[218:221], v249 offset:2048
	ds_read_b128 v[224:227], v249 offset:4096
	ds_read_b128 v[228:231], v249 offset:6144
	v_mfma_f32_16x16x32_bf16 v[62:65], v[232:235], v[196:199], v[62:65]
	s_mov_b32 m0, s96
	v_mfma_f32_16x16x32_bf16 v[58:61], v[236:239], v[196:199], v[58:61]
	global_load_lds_dwordx4 v140, s[98:99]
	v_mfma_f32_16x16x32_bf16 v[54:57], v[240:243], v[196:199], v[54:57]
	s_add_u32 m0, m0, 0x2000
	v_mfma_f32_16x16x32_bf16 v[50:53], v[244:247], v[196:199], v[50:53]
	global_load_lds_dwordx4 v152, s[98:99]
	v_mfma_f32_16x16x32_bf16 v[46:49], v[232:235], v[200:203], v[46:49]
	s_add_u32 m0, m0, 0x2000
	v_mfma_f32_16x16x32_bf16 v[42:45], v[236:239], v[200:203], v[42:45]
	global_load_lds_dwordx4 v156, s[98:99]
	v_mfma_f32_16x16x32_bf16 v[38:41], v[240:243], v[200:203], v[38:41]
	s_add_u32 m0, m0, 0x2000
	v_mfma_f32_16x16x32_bf16 v[34:37], v[244:247], v[200:203], v[34:37]
	global_load_lds_dwordx4 v160, s[98:99]
	v_mfma_f32_16x16x32_bf16 v[30:33], v[232:235], v[204:207], v[30:33]
	s_add_u32 m0, m0, 0xa000
	v_mfma_f32_16x16x32_bf16 v[26:29], v[236:239], v[204:207], v[26:29]
	global_load_lds_dwordx4 v164, s[100:101]
	v_mfma_f32_16x16x32_bf16 v[22:25], v[240:243], v[204:207], v[22:25]
	s_add_u32 m0, m0, 0x2000
	v_mfma_f32_16x16x32_bf16 v[18:21], v[244:247], v[204:207], v[18:21]
	global_load_lds_dwordx4 v168, s[100:101]
	v_mfma_f32_16x16x32_bf16 v[14:17], v[232:235], v[208:211], v[14:17]
	s_add_u32 m0, m0, 0x2000
	v_mfma_f32_16x16x32_bf16 v[10:13], v[236:239], v[208:211], v[10:13]
	global_load_lds_dwordx4 v172, s[100:101]
	v_mfma_f32_16x16x32_bf16 v[6:9], v[240:243], v[208:211], v[6:9]
	s_add_u32 m0, m0, 0x2000
	v_mfma_f32_16x16x32_bf16 v[2:5], v[244:247], v[208:211], v[2:5]
	global_load_lds_dwordx4 v176, s[100:101]
	s_branch .Lg2_p4_loop

.LBB0_354:
	s_mul_hi_i32 s0, s3, 0x2e8ba2e9
	s_lshr_b32 s1, s0, 31
	s_ashr_i32 s0, s0, 4
	s_add_i32 s40, s0, s1
	s_lshl_b32 s0, s40, 2
	s_sub_i32 s1, 33, s0
	s_min_u32 s1, s1, 4
	v_cvt_f32_ubyte0_e32 v2, s1
	v_rcp_iflag_f32_e32 v2, v2
	s_sub_i32 s41, 0, s1
	s_mul_i32 s37, s40, 0xffffffa8
	s_add_i32 s37, s37, s3
	v_mul_f32_e32 v2, 0x4f7ffffe, v2
	v_cvt_u32_f32_e32 v2, v2
	s_abs_i32 s39, s37
	s_ashr_i32 s38, s37, 31
	s_mulk_i32 s40, 0x54
	v_readfirstlane_b32 s42, v2
	s_mul_i32 s41, s41, s42
	s_mul_hi_u32 s41, s42, s41
	s_add_i32 s42, s42, s41
	s_mul_hi_u32 s41, s39, s42
	s_mul_i32 s42, s41, s1
	s_sub_i32 s39, s39, s42
	s_add_i32 s42, s41, 1
	s_sub_i32 s43, s39, s1
	s_cmp_ge_u32 s39, s1
	s_cselect_b32 s41, s42, s41
	s_cselect_b32 s39, s43, s39
	s_add_i32 s42, s41, 1
	s_cmp_ge_u32 s39, s1
	s_cselect_b32 s39, s42, s41
	s_xor_b32 s39, s39, s38
	s_sub_i32 s38, s39, s38
	s_add_i32 s0, s0, s6
	s_mul_i32 s41, s1, s38
	s_add_i32 s0, s0, s37
	s_sub_i32 s0, s0, s41
	s_lshl_b32 s37, s0, 8
	v_or_b32_e32 v2, s37, v1
	v_ashrrev_i32_e32 v3, 31, v2
	v_lshlrev_b64 v[2:3], 11, v[2:3]
	v_lshl_add_u64 v[2:3], v[132:133], 0, v[2:3]
	v_add_co_u32_e32 v6, vcc, s9, v2
	s_lshl_b32 s38, s38, 8
	s_nop 0
	v_addc_co_u32_e32 v7, vcc, 0, v3, vcc
	v_or_b32_e32 v4, s38, v1
	global_load_dwordx4 v[20:23], v[2:3], off
	global_load_dwordx4 v[24:27], v[6:7], off
	v_add_co_u32_e32 v6, vcc, s10, v2
	v_ashrrev_i32_e32 v5, 31, v4
	s_nop 0
	v_addc_co_u32_e32 v7, vcc, 0, v3, vcc
	v_lshlrev_b64 v[52:53], 11, v[4:5]
	v_add_co_u32_e32 v2, vcc, s11, v2
	v_lshl_add_u64 v[4:5], v[134:135], 0, v[52:53]
	s_nop 0
	v_addc_co_u32_e32 v3, vcc, 0, v3, vcc
	global_load_dwordx4 v[28:31], v[6:7], off
	global_load_dwordx4 v[32:35], v[2:3], off
	v_add_co_u32_e32 v2, vcc, s9, v4
	s_waitcnt vmcnt(63) expcnt(7) lgkmcnt(15)
	s_nop 0
	v_addc_co_u32_e32 v3, vcc, 0, v5, vcc
	s_barrier
	global_load_dwordx4 v[36:39], v[4:5], off
	global_load_dwordx4 v[40:43], v[2:3], off
	v_add_co_u32_e32 v2, vcc, s10, v4
	s_sub_i32 s41, s8, s41
	s_nop 0
	v_addc_co_u32_e32 v3, vcc, 0, v5, vcc
	v_add_co_u32_e32 v4, vcc, s11, v4
	s_sub_i32 s40, s41, s40
	s_nop 0
	v_addc_co_u32_e32 v5, vcc, 0, v5, vcc
	global_load_dwordx4 v[44:47], v[2:3], off
	global_load_dwordx4 v[48:51], v[4:5], off
	v_lshl_add_u32 v54, s40, 8, v1
	v_ashrrev_i32_e32 v55, 31, v54
	v_lshl_add_u64 v[140:141], v[138:139], 0, v[52:53]
	v_lshlrev_b64 v[52:53], 11, v[54:55]
	s_mov_b64 s[0:1], 0
	s_mov_b32 s39, 0
	v_mov_b32_e32 v2, 0
	v_mov_b32_e32 v3, v131
	v_mov_b32_e32 v4, v131
	v_mov_b32_e32 v5, v131
	v_mov_b32_e32 v6, 0
	v_mov_b32_e32 v7, v131
	v_mov_b32_e32 v8, v131
	v_mov_b32_e32 v9, v131
	v_mov_b32_e32 v10, 0
	v_mov_b32_e32 v11, v131
	v_mov_b32_e32 v12, v131
	v_mov_b32_e32 v13, v131
	v_mov_b32_e32 v14, 0
	v_mov_b32_e32 v15, v131
	v_mov_b32_e32 v16, v131
	v_mov_b32_e32 v17, v131
	v_mov_b32_e32 v18, 0
	v_lshl_add_u64 v[142:143], v[138:139], 0, v[52:53]
	v_mov_b32_e32 v19, v131
	v_mov_b32_e32 v52, v131
	v_mov_b32_e32 v53, v131
	v_mov_b32_e32 v54, 0
	v_mov_b32_e32 v55, v131
	v_mov_b32_e32 v56, v131
	v_mov_b32_e32 v57, v131
	v_mov_b32_e32 v58, 0
	v_mov_b32_e32 v59, v131
	v_mov_b32_e32 v60, v131
	v_mov_b32_e32 v61, v131
	v_mov_b32_e32 v62, 0
	v_mov_b32_e32 v63, v131
	v_mov_b32_e32 v64, v131
	v_mov_b32_e32 v65, v131
	v_mov_b32_e32 v66, 0
	v_mov_b32_e32 v67, v131
	v_mov_b32_e32 v68, v131
	v_mov_b32_e32 v69, v131
	v_mov_b32_e32 v70, 0
	v_mov_b32_e32 v71, v131
	v_mov_b32_e32 v72, v131
	v_mov_b32_e32 v73, v131
	v_mov_b32_e32 v74, 0
	s_waitcnt vmcnt(7)
	ds_write_b128 v144, v[20:23]
	s_waitcnt vmcnt(6)
	ds_write_b128 v144, v[24:27] offset:8192
	s_waitcnt vmcnt(5)
	ds_write_b128 v144, v[28:31] offset:16384
	s_waitcnt vmcnt(4)
	ds_write_b128 v144, v[32:35] offset:24576
	s_waitcnt vmcnt(3)
	ds_write_b128 v145, v[36:39]
	s_waitcnt vmcnt(2)
	ds_write_b128 v145, v[40:43] offset:8192
	s_waitcnt vmcnt(1)
	ds_write_b128 v145, v[44:47] offset:16384
	s_waitcnt vmcnt(0)
	ds_write_b128 v145, v[48:51] offset:24576
	v_mov_b32_e32 v20, v131
	v_mov_b32_e32 v21, v131
	v_mov_b32_e32 v22, 0
	v_mov_b32_e32 v23, v131
	v_mov_b32_e32 v24, v131
	v_mov_b32_e32 v25, v131
	v_mov_b32_e32 v26, 0
	v_mov_b32_e32 v27, v131
	v_mov_b32_e32 v28, v131
	v_mov_b32_e32 v29, v131
	v_mov_b32_e32 v30, 0
	v_mov_b32_e32 v31, v131
	v_mov_b32_e32 v32, v131
	v_mov_b32_e32 v33, v131
	v_mov_b32_e32 v34, 0
	v_mov_b32_e32 v35, v131
	v_mov_b32_e32 v36, v131
	v_mov_b32_e32 v37, v131
	v_mov_b32_e32 v38, 0
	v_mov_b32_e32 v39, v131
	v_mov_b32_e32 v40, v131
	v_mov_b32_e32 v41, v131
	v_mov_b32_e32 v42, 0
	v_mov_b32_e32 v43, v131
	v_mov_b32_e32 v44, v131
	v_mov_b32_e32 v45, v131
	v_mov_b32_e32 v46, 0
	v_mov_b32_e32 v47, v131
	v_mov_b32_e32 v48, v131
	v_mov_b32_e32 v49, v131
	v_mov_b32_e32 v50, 0
	v_mov_b32_e32 v51, v131
	v_mov_b32_e32 v75, v131
	v_mov_b32_e32 v76, v131
	v_mov_b32_e32 v77, v131
	v_mov_b32_e32 v78, 0
	v_mov_b32_e32 v79, v131
	v_mov_b32_e32 v80, v131
	v_mov_b32_e32 v81, v131
	v_mov_b32_e32 v82, 0
	v_mov_b32_e32 v83, v131
	v_mov_b32_e32 v84, v131
	v_mov_b32_e32 v85, v131
	v_mov_b32_e32 v86, 0
	v_mov_b32_e32 v87, v131
	v_mov_b32_e32 v88, v131
	v_mov_b32_e32 v89, v131
	v_mov_b32_e32 v90, 0
	v_mov_b32_e32 v91, v131
	v_mov_b32_e32 v92, v131
	v_mov_b32_e32 v93, v131
	v_mov_b32_e32 v94, 0
	v_mov_b32_e32 v95, v131
	v_mov_b32_e32 v96, v131
	v_mov_b32_e32 v97, v131
	v_mov_b32_e32 v98, 0
	v_mov_b32_e32 v99, v131
	v_mov_b32_e32 v100, v131
	v_mov_b32_e32 v101, v131
	v_mov_b32_e32 v102, 0
	v_mov_b32_e32 v103, v131
	v_mov_b32_e32 v104, v131
	v_mov_b32_e32 v105, v131
	v_mov_b32_e32 v106, 0
	v_mov_b32_e32 v107, v131
	v_mov_b32_e32 v108, v131
	v_mov_b32_e32 v109, v131
	v_mov_b32_e32 v110, 0
	v_mov_b32_e32 v111, v131
	v_mov_b32_e32 v112, v131
	v_mov_b32_e32 v113, v131
	v_mov_b32_e32 v114, 0
	v_mov_b32_e32 v115, v131
	v_mov_b32_e32 v116, v131
	v_mov_b32_e32 v117, v131
	v_mov_b32_e32 v118, 0
	v_mov_b32_e32 v119, v131
	v_mov_b32_e32 v120, v131
	v_mov_b32_e32 v121, v131
	v_mov_b32_e32 v122, 0
	v_mov_b32_e32 v123, v131
	v_mov_b32_e32 v124, v131
	v_mov_b32_e32 v125, v131
	v_mov_b32_e32 v126, 0
	v_mov_b32_e32 v127, v131
	v_mov_b32_e32 v128, v131
	v_mov_b32_e32 v129, v131
	s_waitcnt lgkmcnt(0)
	s_barrier
	s_movk_i32 s97, 0x70
	v_readfirstlane_b32 s98, v142
	v_readfirstlane_b32 s99, v143
	v_subrev_u32_e32 v215, s98, v142
	v_bfi_b32 v215, s97, v144, v215
	v_add_u32_e32 v150, s12, v215
	v_add_u32_e32 v154, s13, v215
	v_add_u32_e32 v158, s14, v215
	v_add_u32_e32 v162, s15, v215
	s_add_u32 s98, s98, s0
	s_addc_u32 s99, s99, s1
	s_add_u32 s98, s98, 0x80
	s_addc_u32 s99, s99, 0
	v_readfirstlane_b32 s100, v140
	v_readfirstlane_b32 s101, v141
	v_subrev_u32_e32 v252, s100, v140
	v_bfi_b32 v252, s97, v144, v252
	v_add_u32_e32 v166, s16, v252
	v_add_u32_e32 v170, s17, v252
	v_add_u32_e32 v174, s28, v252
	v_add_u32_e32 v178, s29, v252
	s_add_u32 s100, s100, s0
	s_addc_u32 s101, s101, s1
	s_add_u32 s100, s100, 0x80
	s_addc_u32 s101, s101, 0
	v_readfirstlane_b32 s96, v144
	s_and_b32 s96, s96, 0xfc00
	s_xor_b32 s96, s96, 0x8000
	s_mov_b32 m0, s96
	s_nop 0
	global_load_lds_dwordx4 v150, s[98:99]
	s_add_u32 m0, m0, 0x2000
	s_nop 0
	global_load_lds_dwordx4 v154, s[98:99]
	s_add_u32 m0, m0, 0x2000
	s_nop 0
	global_load_lds_dwordx4 v158, s[98:99]
	s_add_u32 m0, m0, 0x2000
	s_nop 0
	global_load_lds_dwordx4 v162, s[98:99]
	s_add_u32 m0, m0, 0xa000
	s_nop 0
	global_load_lds_dwordx4 v166, s[100:101]
	s_add_u32 m0, m0, 0x2000
	s_nop 0
	global_load_lds_dwordx4 v170, s[100:101]
	s_add_u32 m0, m0, 0x2000
	s_nop 0
	global_load_lds_dwordx4 v174, s[100:101]
	s_add_u32 m0, m0, 0x2000
	s_nop 0
	global_load_lds_dwordx4 v178, s[100:101]
	v_mov_b32_e32 v214, v146
	v_mov_b32_e32 v223, v147
	ds_read_b128 v[182:185], v214
	ds_read_b128 v[186:189], v214 offset:2048
	ds_read_b128 v[190:193], v214 offset:4096
	ds_read_b128 v[194:197], v214 offset:6144
	ds_read_b128 v[218:221], v223
	ds_read_b128 v[224:227], v223 offset:2048
	ds_read_b128 v[228:231], v223 offset:4096
	ds_read_b128 v[232:235], v223 offset:6144
.Lg2_p6_loop:
	ds_read_b128 v[198:201], v214 offset:8192
	ds_read_b128 v[202:205], v214 offset:10240
	ds_read_b128 v[206:209], v214 offset:12288
	ds_read_b128 v[210:213], v214 offset:14336
	s_waitcnt lgkmcnt(4)
	v_mfma_f32_16x16x32_bf16 v[126:129], v[218:221], v[182:185], v[126:129]
	v_mfma_f32_16x16x32_bf16 v[122:125], v[224:227], v[182:185], v[122:125]
	v_mfma_f32_16x16x32_bf16 v[118:121], v[228:231], v[182:185], v[118:121]
	v_mfma_f32_16x16x32_bf16 v[114:117], v[232:235], v[182:185], v[114:117]
	v_mfma_f32_16x16x32_bf16 v[110:113], v[218:221], v[186:189], v[110:113]
	v_mfma_f32_16x16x32_bf16 v[106:109], v[224:227], v[186:189], v[106:109]
	v_mfma_f32_16x16x32_bf16 v[102:105], v[228:231], v[186:189], v[102:105]
	v_mfma_f32_16x16x32_bf16 v[98:101], v[232:235], v[186:189], v[98:101]
	v_mfma_f32_16x16x32_bf16 v[94:97], v[218:221], v[190:193], v[94:97]
	v_mfma_f32_16x16x32_bf16 v[90:93], v[224:227], v[190:193], v[90:93]
	v_mfma_f32_16x16x32_bf16 v[86:89], v[228:231], v[190:193], v[86:89]
	v_mfma_f32_16x16x32_bf16 v[82:85], v[232:235], v[190:193], v[82:85]
	v_mfma_f32_16x16x32_bf16 v[78:81], v[218:221], v[194:197], v[78:81]
	v_mfma_f32_16x16x32_bf16 v[74:77], v[224:227], v[194:197], v[74:77]
	v_mfma_f32_16x16x32_bf16 v[70:73], v[228:231], v[194:197], v[70:73]
	v_mfma_f32_16x16x32_bf16 v[66:69], v[232:235], v[194:197], v[66:69]
	ds_read_b128 v[182:185], v216
	ds_read_b128 v[186:189], v216 offset:2048
	ds_read_b128 v[190:193], v216 offset:4096
	ds_read_b128 v[194:197], v216 offset:6144
	ds_read_b128 v[236:239], v217
	ds_read_b128 v[240:243], v217 offset:2048
	ds_read_b128 v[244:247], v217 offset:4096
	ds_read_b128 v[248:251], v217 offset:6144
	s_waitcnt lgkmcnt(8)
	v_mfma_f32_16x16x32_bf16 v[62:65], v[218:221], v[198:201], v[62:65]
	v_mfma_f32_16x16x32_bf16 v[58:61], v[224:227], v[198:201], v[58:61]
	v_mfma_f32_16x16x32_bf16 v[54:57], v[228:231], v[198:201], v[54:57]
	v_mfma_f32_16x16x32_bf16 v[50:53], v[232:235], v[198:201], v[50:53]
	v_mfma_f32_16x16x32_bf16 v[46:49], v[218:221], v[202:205], v[46:49]
	v_mfma_f32_16x16x32_bf16 v[42:45], v[224:227], v[202:205], v[42:45]
	v_mfma_f32_16x16x32_bf16 v[38:41], v[228:231], v[202:205], v[38:41]
	v_mfma_f32_16x16x32_bf16 v[34:37], v[232:235], v[202:205], v[34:37]
	v_mfma_f32_16x16x32_bf16 v[30:33], v[218:221], v[206:209], v[30:33]
	v_mfma_f32_16x16x32_bf16 v[26:29], v[224:227], v[206:209], v[26:29]
	v_mfma_f32_16x16x32_bf16 v[22:25], v[228:231], v[206:209], v[22:25]
	v_mfma_f32_16x16x32_bf16 v[18:21], v[232:235], v[206:209], v[18:21]
	v_mfma_f32_16x16x32_bf16 v[14:17], v[218:221], v[210:213], v[14:17]
	v_mfma_f32_16x16x32_bf16 v[10:13], v[224:227], v[210:213], v[10:13]
	v_mfma_f32_16x16x32_bf16 v[6:9], v[228:231], v[210:213], v[6:9]
	v_mfma_f32_16x16x32_bf16 v[2:5], v[232:235], v[210:213], v[2:5]
	ds_read_b128 v[198:201], v216 offset:8192
	ds_read_b128 v[202:205], v216 offset:10240
	ds_read_b128 v[206:209], v216 offset:12288
	ds_read_b128 v[210:213], v216 offset:14336
	s_waitcnt lgkmcnt(4)
	v_mfma_f32_16x16x32_bf16 v[126:129], v[236:239], v[182:185], v[126:129]
	v_mfma_f32_16x16x32_bf16 v[122:125], v[240:243], v[182:185], v[122:125]
	v_mfma_f32_16x16x32_bf16 v[118:121], v[244:247], v[182:185], v[118:121]
	v_mfma_f32_16x16x32_bf16 v[114:117], v[248:251], v[182:185], v[114:117]
	v_mfma_f32_16x16x32_bf16 v[110:113], v[236:239], v[186:189], v[110:113]
	v_mfma_f32_16x16x32_bf16 v[106:109], v[240:243], v[186:189], v[106:109]
	v_mfma_f32_16x16x32_bf16 v[102:105], v[244:247], v[186:189], v[102:105]
	v_mfma_f32_16x16x32_bf16 v[98:101], v[248:251], v[186:189], v[98:101]
	v_mfma_f32_16x16x32_bf16 v[94:97], v[236:239], v[190:193], v[94:97]
	v_mfma_f32_16x16x32_bf16 v[90:93], v[240:243], v[190:193], v[90:93]
	v_mfma_f32_16x16x32_bf16 v[86:89], v[244:247], v[190:193], v[86:89]
	v_mfma_f32_16x16x32_bf16 v[82:85], v[248:251], v[190:193], v[82:85]
	v_mfma_f32_16x16x32_bf16 v[78:81], v[236:239], v[194:197], v[78:81]
	v_mfma_f32_16x16x32_bf16 v[74:77], v[240:243], v[194:197], v[74:77]
	v_mfma_f32_16x16x32_bf16 v[70:73], v[244:247], v[194:197], v[70:73]
	v_mfma_f32_16x16x32_bf16 v[66:69], v[248:251], v[194:197], v[66:69]
	s_waitcnt vmcnt(0)
	s_waitcnt lgkmcnt(0)
	s_barrier
	s_add_u32 s0, s0, 0x80
	s_addc_u32 s1, s1, 0
	s_add_u32 s98, s98, 0x80
	s_addc_u32 s99, s99, 0
	s_add_u32 s100, s100, 0x80
	s_addc_u32 s101, s101, 0
	s_cmpk_eq_i32 s0, 0x780
	s_cbranch_scc1 .Lg2_p6_tail
	v_xor_b32_e32 v214, 0x8000, v214
	v_xor_b32_e32 v223, 0x8000, v223
	v_xor_b32_e32 v216, 0x8000, v216
	v_xor_b32_e32 v217, 0x8000, v217
	s_xor_b32 s96, s96, 0x8000
	ds_read_b128 v[182:185], v214
	ds_read_b128 v[186:189], v214 offset:2048
	ds_read_b128 v[190:193], v214 offset:4096
	ds_read_b128 v[194:197], v214 offset:6144
	ds_read_b128 v[218:221], v223
	ds_read_b128 v[224:227], v223 offset:2048
	ds_read_b128 v[228:231], v223 offset:4096
	ds_read_b128 v[232:235], v223 offset:6144
	v_mfma_f32_16x16x32_bf16 v[62:65], v[236:239], v[198:201], v[62:65]
	s_mov_b32 m0, s96
	v_mfma_f32_16x16x32_bf16 v[58:61], v[240:243], v[198:201], v[58:61]
	global_load_lds_dwordx4 v150, s[98:99]
	v_mfma_f32_16x16x32_bf16 v[54:57], v[244:247], v[198:201], v[54:57]
	s_add_u32 m0, m0, 0x2000
	v_mfma_f32_16x16x32_bf16 v[50:53], v[248:251], v[198:201], v[50:53]
	global_load_lds_dwordx4 v154, s[98:99]
	v_mfma_f32_16x16x32_bf16 v[46:49], v[236:239], v[202:205], v[46:49]
	s_add_u32 m0, m0, 0x2000
	v_mfma_f32_16x16x32_bf16 v[42:45], v[240:243], v[202:205], v[42:45]
	global_load_lds_dwordx4 v158, s[98:99]
	v_mfma_f32_16x16x32_bf16 v[38:41], v[244:247], v[202:205], v[38:41]
	s_add_u32 m0, m0, 0x2000
	v_mfma_f32_16x16x32_bf16 v[34:37], v[248:251], v[202:205], v[34:37]
	global_load_lds_dwordx4 v162, s[98:99]
	v_mfma_f32_16x16x32_bf16 v[30:33], v[236:239], v[206:209], v[30:33]
	s_add_u32 m0, m0, 0xa000
	v_mfma_f32_16x16x32_bf16 v[26:29], v[240:243], v[206:209], v[26:29]
	global_load_lds_dwordx4 v166, s[100:101]
	v_mfma_f32_16x16x32_bf16 v[22:25], v[244:247], v[206:209], v[22:25]
	s_add_u32 m0, m0, 0x2000
	v_mfma_f32_16x16x32_bf16 v[18:21], v[248:251], v[206:209], v[18:21]
	global_load_lds_dwordx4 v170, s[100:101]
	v_mfma_f32_16x16x32_bf16 v[14:17], v[236:239], v[210:213], v[14:17]
	s_add_u32 m0, m0, 0x2000
	v_mfma_f32_16x16x32_bf16 v[10:13], v[240:243], v[210:213], v[10:13]
	global_load_lds_dwordx4 v174, s[100:101]
	v_mfma_f32_16x16x32_bf16 v[6:9], v[244:247], v[210:213], v[6:9]
	s_add_u32 m0, m0, 0x2000
	v_mfma_f32_16x16x32_bf16 v[2:5], v[248:251], v[210:213], v[2:5]
	global_load_lds_dwordx4 v178, s[100:101]
	s_branch .Lg2_p6_loop

.LBB0_378:
	s_lshl_b32 s47, s45, 8
	v_or_b32_e32 v27, s47, v1
	v_mad_i64_i32 v[2:3], s[8:9], v27, s12, v[130:131]
	v_add_co_u32_e32 v6, vcc, 0x58000, v2
	s_lshl_b32 s46, s44, 8
	s_nop 0
	v_addc_co_u32_e32 v7, vcc, 0, v3, vcc
	global_load_dwordx4 v[28:31], v[2:3], off
	global_load_dwordx4 v[32:35], v[6:7], off
	v_add_co_u32_e32 v6, vcc, 0xb0000, v2
	v_or_b32_e32 v60, s46, v1
	s_nop 0
	v_addc_co_u32_e32 v7, vcc, 0, v3, vcc
	v_add_co_u32_e32 v2, vcc, 0x108000, v2
	v_mad_i64_i32 v[4:5], s[8:9], v60, s12, v[132:133]
	s_nop 0
	v_addc_co_u32_e32 v3, vcc, 0, v3, vcc
	global_load_dwordx4 v[36:39], v[6:7], off
	global_load_dwordx4 v[40:43], v[2:3], off
	v_add_co_u32_e32 v2, vcc, s13, v4
	s_waitcnt vmcnt(63) expcnt(7) lgkmcnt(15)
	s_nop 0
	v_addc_co_u32_e32 v3, vcc, 0, v5, vcc
	s_barrier
	global_load_dwordx4 v[44:47], v[4:5], off
	global_load_dwordx4 v[48:51], v[2:3], off
	v_add_co_u32_e32 v2, vcc, s14, v4
	s_mov_b32 s52, 0
	s_nop 0
	v_addc_co_u32_e32 v3, vcc, 0, v5, vcc
	v_add_co_u32_e32 v4, vcc, s15, v4
	s_mov_b64 s[8:9], 0
	s_nop 0
	v_addc_co_u32_e32 v5, vcc, 0, v5, vcc
	global_load_dwordx4 v[52:55], v[2:3], off
	global_load_dwordx4 v[56:59], v[4:5], off
	v_mov_b32_e32 v2, 0
	v_mov_b32_e32 v3, v2
	v_mov_b32_e32 v4, v2
	v_mov_b32_e32 v5, v2
	v_mov_b32_e32 v6, v2
	v_mov_b32_e32 v7, v2
	v_mov_b32_e32 v8, v2
	v_mov_b32_e32 v9, v2
	v_mov_b32_e32 v10, v2
	v_mov_b32_e32 v11, v2
	v_mov_b32_e32 v12, v2
	v_mov_b32_e32 v13, v2
	v_mov_b32_e32 v14, v2
	v_mov_b32_e32 v15, v2
	v_mov_b32_e32 v16, v2
	v_mov_b32_e32 v17, v2
	v_mov_b32_e32 v18, v2
	v_mov_b32_e32 v19, v2
	v_mov_b32_e32 v20, v2
	v_mov_b32_e32 v21, v2
	v_mov_b32_e32 v22, v2
	v_mov_b32_e32 v23, v2
	v_mov_b32_e32 v24, v2
	v_mov_b32_e32 v25, v2
	v_mov_b32_e32 v26, v2
	v_mad_i64_i32 v[136:137], s[56:57], v27, s12, v[134:135]
	v_mad_i64_i32 v[138:139], s[56:57], v60, s12, v[134:135]
	v_mov_b32_e32 v27, v2
	v_mov_b32_e32 v60, v2
	v_mov_b32_e32 v61, v2
	v_mov_b32_e32 v62, v2
	v_mov_b32_e32 v63, v2
	v_mov_b32_e32 v64, v2
	v_mov_b32_e32 v65, v2
	v_mov_b32_e32 v66, v2
	v_mov_b32_e32 v67, v2
	v_mov_b32_e32 v68, v2
	v_mov_b32_e32 v69, v2
	v_mov_b32_e32 v70, v2
	v_mov_b32_e32 v71, v2
	v_mov_b32_e32 v72, v2
	v_mov_b32_e32 v73, v2
	v_mov_b32_e32 v74, v2
	v_mov_b32_e32 v75, v2
	v_mov_b32_e32 v76, v2
	v_mov_b32_e32 v77, v2
	v_mov_b32_e32 v78, v2
	v_mov_b32_e32 v79, v2
	v_mov_b32_e32 v80, v2
	v_mov_b32_e32 v81, v2
	v_mov_b32_e32 v82, v2
	s_waitcnt vmcnt(7)
	ds_write_b128 v146, v[28:31]
	s_waitcnt vmcnt(6)
	ds_write_b128 v146, v[32:35] offset:8192
	s_waitcnt vmcnt(5)
	ds_write_b128 v146, v[36:39] offset:16384
	s_waitcnt vmcnt(4)
	ds_write_b128 v146, v[40:43] offset:24576
	s_waitcnt vmcnt(3)
	ds_write_b128 v147, v[44:47]
	s_waitcnt vmcnt(2)
	ds_write_b128 v147, v[48:51] offset:8192
	s_waitcnt vmcnt(1)
	ds_write_b128 v147, v[52:55] offset:16384
	s_waitcnt vmcnt(0)
	ds_write_b128 v147, v[56:59] offset:24576
	v_mov_b32_e32 v28, v2
	v_mov_b32_e32 v29, v2
	v_mov_b32_e32 v30, v2
	v_mov_b32_e32 v31, v2
	v_mov_b32_e32 v32, v2
	v_mov_b32_e32 v33, v2
	v_mov_b32_e32 v34, v2
	v_mov_b32_e32 v35, v2
	v_mov_b32_e32 v36, v2
	v_mov_b32_e32 v37, v2
	v_mov_b32_e32 v38, v2
	v_mov_b32_e32 v39, v2
	v_mov_b32_e32 v40, v2
	v_mov_b32_e32 v41, v2
	v_mov_b32_e32 v42, v2
	v_mov_b32_e32 v43, v2
	v_mov_b32_e32 v44, v2
	v_mov_b32_e32 v45, v2
	v_mov_b32_e32 v46, v2
	v_mov_b32_e32 v47, v2
	v_mov_b32_e32 v48, v2
	v_mov_b32_e32 v49, v2
	v_mov_b32_e32 v50, v2
	v_mov_b32_e32 v51, v2
	v_mov_b32_e32 v52, v2
	v_mov_b32_e32 v53, v2
	v_mov_b32_e32 v54, v2
	v_mov_b32_e32 v55, v2
	v_mov_b32_e32 v56, v2
	v_mov_b32_e32 v57, v2
	v_mov_b32_e32 v58, v2
	v_mov_b32_e32 v59, v2
	v_mov_b32_e32 v83, v2
	v_mov_b32_e32 v84, v2
	v_mov_b32_e32 v85, v2
	v_mov_b32_e32 v86, v2
	v_mov_b32_e32 v87, v2
	v_mov_b32_e32 v88, v2
	v_mov_b32_e32 v89, v2
	v_mov_b32_e32 v90, v2
	v_mov_b32_e32 v91, v2
	v_mov_b32_e32 v92, v2
	v_mov_b32_e32 v93, v2
	v_mov_b32_e32 v94, v2
	v_mov_b32_e32 v95, v2
	v_mov_b32_e32 v96, v2
	v_mov_b32_e32 v97, v2
	v_mov_b32_e32 v98, v2
	v_mov_b32_e32 v99, v2
	v_mov_b32_e32 v100, v2
	v_mov_b32_e32 v101, v2
	v_mov_b32_e32 v102, v2
	v_mov_b32_e32 v103, v2
	v_mov_b32_e32 v104, v2
	v_mov_b32_e32 v105, v2
	v_mov_b32_e32 v106, v2
	v_mov_b32_e32 v107, v2
	v_mov_b32_e32 v108, v2
	v_mov_b32_e32 v109, v2
	v_mov_b32_e32 v110, v2
	v_mov_b32_e32 v111, v2
	v_mov_b32_e32 v112, v2
	v_mov_b32_e32 v113, v2
	v_mov_b32_e32 v114, v2
	v_mov_b32_e32 v115, v2
	v_mov_b32_e32 v116, v2
	v_mov_b32_e32 v117, v2
	v_mov_b32_e32 v118, v2
	v_mov_b32_e32 v119, v2
	v_mov_b32_e32 v120, v2
	v_mov_b32_e32 v121, v2
	v_mov_b32_e32 v122, v2
	v_mov_b32_e32 v123, v2
	v_mov_b32_e32 v124, v2
	v_mov_b32_e32 v125, v2
	v_mov_b32_e32 v126, v2
	v_mov_b32_e32 v127, v2
	v_mov_b32_e32 v128, v2
	v_mov_b32_e32 v129, v2
	s_waitcnt lgkmcnt(0)
	s_barrier
	s_movk_i32 s97, 0x70
	v_readfirstlane_b32 s98, v136
	v_readfirstlane_b32 s99, v137
	v_subrev_u32_e32 v248, s98, v136
	v_bfi_b32 v248, s97, v146, v248
	v_add_u32_e32 v140, s16, v248
	v_add_u32_e32 v152, s17, v248
	v_add_u32_e32 v156, s28, v248
	v_add_u32_e32 v160, s29, v248
	s_add_u32 s98, s98, s8
	s_addc_u32 s99, s99, s9
	s_add_u32 s98, s98, 0x80
	s_addc_u32 s99, s99, 0
	v_readfirstlane_b32 s100, v138
	v_readfirstlane_b32 s101, v139
	v_subrev_u32_e32 v250, s100, v138
	v_bfi_b32 v250, s97, v146, v250
	v_add_u32_e32 v164, s36, v250
	v_add_u32_e32 v168, s37, v250
	v_add_u32_e32 v172, s38, v250
	v_add_u32_e32 v176, s39, v250
	s_add_u32 s100, s100, s8
	s_addc_u32 s101, s101, s9
	s_add_u32 s100, s100, 0x80
	s_addc_u32 s101, s101, 0
	v_readfirstlane_b32 s96, v146
	s_and_b32 s96, s96, 0xfc00
	s_xor_b32 s96, s96, 0x8000
	s_mov_b32 m0, s96
	s_nop 0
	global_load_lds_dwordx4 v140, s[98:99]
	s_add_u32 m0, m0, 0x2000
	s_nop 0
	global_load_lds_dwordx4 v152, s[98:99]
	s_add_u32 m0, m0, 0x2000
	s_nop 0
	global_load_lds_dwordx4 v156, s[98:99]
	s_add_u32 m0, m0, 0x2000
	s_nop 0
	global_load_lds_dwordx4 v160, s[98:99]
	s_add_u32 m0, m0, 0xa000
	s_nop 0
	global_load_lds_dwordx4 v164, s[100:101]
	s_add_u32 m0, m0, 0x2000
	s_nop 0
	global_load_lds_dwordx4 v168, s[100:101]
	s_add_u32 m0, m0, 0x2000
	s_nop 0
	global_load_lds_dwordx4 v172, s[100:101]
	s_add_u32 m0, m0, 0x2000
	s_nop 0
	global_load_lds_dwordx4 v176, s[100:101]
	v_mov_b32_e32 v223, v148
	v_mov_b32_e32 v249, v149
	ds_read_b128 v[180:183], v223
	ds_read_b128 v[184:187], v223 offset:2048
	ds_read_b128 v[188:191], v223 offset:4096
	ds_read_b128 v[192:195], v223 offset:6144
	ds_read_b128 v[212:215], v249
	ds_read_b128 v[218:221], v249 offset:2048
	ds_read_b128 v[224:227], v249 offset:4096
	ds_read_b128 v[228:231], v249 offset:6144
.Lg2_p7_loop:
	ds_read_b128 v[196:199], v223 offset:8192
	ds_read_b128 v[200:203], v223 offset:10240
	ds_read_b128 v[204:207], v223 offset:12288
	ds_read_b128 v[208:211], v223 offset:14336
	s_waitcnt lgkmcnt(4)
	v_mfma_f32_16x16x32_bf16 v[126:129], v[212:215], v[180:183], v[126:129]
	v_mfma_f32_16x16x32_bf16 v[122:125], v[218:221], v[180:183], v[122:125]
	v_mfma_f32_16x16x32_bf16 v[118:121], v[224:227], v[180:183], v[118:121]
	v_mfma_f32_16x16x32_bf16 v[114:117], v[228:231], v[180:183], v[114:117]
	v_mfma_f32_16x16x32_bf16 v[110:113], v[212:215], v[184:187], v[110:113]
	v_mfma_f32_16x16x32_bf16 v[106:109], v[218:221], v[184:187], v[106:109]
	v_mfma_f32_16x16x32_bf16 v[102:105], v[224:227], v[184:187], v[102:105]
	v_mfma_f32_16x16x32_bf16 v[98:101], v[228:231], v[184:187], v[98:101]
	v_mfma_f32_16x16x32_bf16 v[94:97], v[212:215], v[188:191], v[94:97]
	v_mfma_f32_16x16x32_bf16 v[90:93], v[218:221], v[188:191], v[90:93]
	v_mfma_f32_16x16x32_bf16 v[86:89], v[224:227], v[188:191], v[86:89]
	v_mfma_f32_16x16x32_bf16 v[82:85], v[228:231], v[188:191], v[82:85]
	v_mfma_f32_16x16x32_bf16 v[78:81], v[212:215], v[192:195], v[78:81]
	v_mfma_f32_16x16x32_bf16 v[74:77], v[218:221], v[192:195], v[74:77]
	v_mfma_f32_16x16x32_bf16 v[70:73], v[224:227], v[192:195], v[70:73]
	v_mfma_f32_16x16x32_bf16 v[66:69], v[228:231], v[192:195], v[66:69]
	ds_read_b128 v[180:183], v216
	ds_read_b128 v[184:187], v216 offset:2048
	ds_read_b128 v[188:191], v216 offset:4096
	ds_read_b128 v[192:195], v216 offset:6144
	ds_read_b128 v[232:235], v217
	ds_read_b128 v[236:239], v217 offset:2048
	ds_read_b128 v[240:243], v217 offset:4096
	ds_read_b128 v[244:247], v217 offset:6144
	s_waitcnt lgkmcnt(8)
	v_mfma_f32_16x16x32_bf16 v[62:65], v[212:215], v[196:199], v[62:65]
	v_mfma_f32_16x16x32_bf16 v[58:61], v[218:221], v[196:199], v[58:61]
	v_mfma_f32_16x16x32_bf16 v[54:57], v[224:227], v[196:199], v[54:57]
	v_mfma_f32_16x16x32_bf16 v[50:53], v[228:231], v[196:199], v[50:53]
	v_mfma_f32_16x16x32_bf16 v[46:49], v[212:215], v[200:203], v[46:49]
	v_mfma_f32_16x16x32_bf16 v[42:45], v[218:221], v[200:203], v[42:45]
	v_mfma_f32_16x16x32_bf16 v[38:41], v[224:227], v[200:203], v[38:41]
	v_mfma_f32_16x16x32_bf16 v[34:37], v[228:231], v[200:203], v[34:37]
	v_mfma_f32_16x16x32_bf16 v[30:33], v[212:215], v[204:207], v[30:33]
	v_mfma_f32_16x16x32_bf16 v[26:29], v[218:221], v[204:207], v[26:29]
	v_mfma_f32_16x16x32_bf16 v[22:25], v[224:227], v[204:207], v[22:25]
	v_mfma_f32_16x16x32_bf16 v[18:21], v[228:231], v[204:207], v[18:21]
	v_mfma_f32_16x16x32_bf16 v[14:17], v[212:215], v[208:211], v[14:17]
	v_mfma_f32_16x16x32_bf16 v[10:13], v[218:221], v[208:211], v[10:13]
	v_mfma_f32_16x16x32_bf16 v[6:9], v[224:227], v[208:211], v[6:9]
	v_mfma_f32_16x16x32_bf16 v[2:5], v[228:231], v[208:211], v[2:5]
	ds_read_b128 v[196:199], v216 offset:8192
	ds_read_b128 v[200:203], v216 offset:10240
	ds_read_b128 v[204:207], v216 offset:12288
	ds_read_b128 v[208:211], v216 offset:14336
	s_waitcnt lgkmcnt(4)
	v_mfma_f32_16x16x32_bf16 v[126:129], v[232:235], v[180:183], v[126:129]
	v_mfma_f32_16x16x32_bf16 v[122:125], v[236:239], v[180:183], v[122:125]
	v_mfma_f32_16x16x32_bf16 v[118:121], v[240:243], v[180:183], v[118:121]
	v_mfma_f32_16x16x32_bf16 v[114:117], v[244:247], v[180:183], v[114:117]
	v_mfma_f32_16x16x32_bf16 v[110:113], v[232:235], v[184:187], v[110:113]
	v_mfma_f32_16x16x32_bf16 v[106:109], v[236:239], v[184:187], v[106:109]
	v_mfma_f32_16x16x32_bf16 v[102:105], v[240:243], v[184:187], v[102:105]
	v_mfma_f32_16x16x32_bf16 v[98:101], v[244:247], v[184:187], v[98:101]
	v_mfma_f32_16x16x32_bf16 v[94:97], v[232:235], v[188:191], v[94:97]
	v_mfma_f32_16x16x32_bf16 v[90:93], v[236:239], v[188:191], v[90:93]
	v_mfma_f32_16x16x32_bf16 v[86:89], v[240:243], v[188:191], v[86:89]
	v_mfma_f32_16x16x32_bf16 v[82:85], v[244:247], v[188:191], v[82:85]
	v_mfma_f32_16x16x32_bf16 v[78:81], v[232:235], v[192:195], v[78:81]
	v_mfma_f32_16x16x32_bf16 v[74:77], v[236:239], v[192:195], v[74:77]
	v_mfma_f32_16x16x32_bf16 v[70:73], v[240:243], v[192:195], v[70:73]
	v_mfma_f32_16x16x32_bf16 v[66:69], v[244:247], v[192:195], v[66:69]
	s_waitcnt vmcnt(0)
	s_waitcnt lgkmcnt(0)
	s_barrier
	s_add_u32 s8, s8, 0x80
	s_addc_u32 s9, s9, 0
	s_add_u32 s98, s98, 0x80
	s_addc_u32 s99, s99, 0
	s_add_u32 s100, s100, 0x80
	s_addc_u32 s101, s101, 0
	s_cmpk_eq_i32 s8, 0x1580
	s_cbranch_scc1 .Lg2_p7_tail
	v_xor_b32_e32 v223, 0x8000, v223
	v_xor_b32_e32 v249, 0x8000, v249
	v_xor_b32_e32 v216, 0x8000, v216
	v_xor_b32_e32 v217, 0x8000, v217
	s_xor_b32 s96, s96, 0x8000
	ds_read_b128 v[180:183], v223
	ds_read_b128 v[184:187], v223 offset:2048
	ds_read_b128 v[188:191], v223 offset:4096
	ds_read_b128 v[192:195], v223 offset:6144
	ds_read_b128 v[212:215], v249
	ds_read_b128 v[218:221], v249 offset:2048
	ds_read_b128 v[224:227], v249 offset:4096
	ds_read_b128 v[228:231], v249 offset:6144
	v_mfma_f32_16x16x32_bf16 v[62:65], v[232:235], v[196:199], v[62:65]
	s_mov_b32 m0, s96
	v_mfma_f32_16x16x32_bf16 v[58:61], v[236:239], v[196:199], v[58:61]
	global_load_lds_dwordx4 v140, s[98:99]
	v_mfma_f32_16x16x32_bf16 v[54:57], v[240:243], v[196:199], v[54:57]
	s_add_u32 m0, m0, 0x2000
	v_mfma_f32_16x16x32_bf16 v[50:53], v[244:247], v[196:199], v[50:53]
	global_load_lds_dwordx4 v152, s[98:99]
	v_mfma_f32_16x16x32_bf16 v[46:49], v[232:235], v[200:203], v[46:49]
	s_add_u32 m0, m0, 0x2000
	v_mfma_f32_16x16x32_bf16 v[42:45], v[236:239], v[200:203], v[42:45]
	global_load_lds_dwordx4 v156, s[98:99]
	v_mfma_f32_16x16x32_bf16 v[38:41], v[240:243], v[200:203], v[38:41]
	s_add_u32 m0, m0, 0x2000
	v_mfma_f32_16x16x32_bf16 v[34:37], v[244:247], v[200:203], v[34:37]
	global_load_lds_dwordx4 v160, s[98:99]
	v_mfma_f32_16x16x32_bf16 v[30:33], v[232:235], v[204:207], v[30:33]
	s_add_u32 m0, m0, 0xa000
	v_mfma_f32_16x16x32_bf16 v[26:29], v[236:239], v[204:207], v[26:29]
	global_load_lds_dwordx4 v164, s[100:101]
	v_mfma_f32_16x16x32_bf16 v[22:25], v[240:243], v[204:207], v[22:25]
	s_add_u32 m0, m0, 0x2000
	v_mfma_f32_16x16x32_bf16 v[18:21], v[244:247], v[204:207], v[18:21]
	global_load_lds_dwordx4 v168, s[100:101]
	v_mfma_f32_16x16x32_bf16 v[14:17], v[232:235], v[208:211], v[14:17]
	s_add_u32 m0, m0, 0x2000
	v_mfma_f32_16x16x32_bf16 v[10:13], v[236:239], v[208:211], v[10:13]
	global_load_lds_dwordx4 v172, s[100:101]
	v_mfma_f32_16x16x32_bf16 v[6:9], v[240:243], v[208:211], v[6:9]
	s_add_u32 m0, m0, 0x2000
	v_mfma_f32_16x16x32_bf16 v[2:5], v[244:247], v[208:211], v[2:5]
	global_load_lds_dwordx4 v176, s[100:101]
	s_branch .Lg2_p7_loop

.LBB0_645:
	s_lshl_b32 s36, s28, 8
	v_or_b32_e32 v2, s36, v1
	v_ashrrev_i32_e32 v3, 31, v2
	v_lshlrev_b64 v[62:63], 11, v[2:3]
	v_lshl_add_u64 v[2:3], v[130:131], 0, v[62:63]
	v_add_co_u32_e32 v6, vcc, 0x20000, v2
	s_lshl_b32 s29, s27, 8
	s_nop 0
	v_addc_co_u32_e32 v7, vcc, 0, v3, vcc
	v_or_b32_e32 v4, s29, v1
	global_load_dwordx4 v[30:33], v[2:3], off
	global_load_dwordx4 v[34:37], v[6:7], off
	v_add_co_u32_e32 v6, vcc, 0x40000, v2
	v_ashrrev_i32_e32 v5, 31, v4
	s_nop 0
	v_addc_co_u32_e32 v7, vcc, 0, v3, vcc
	v_lshlrev_b64 v[64:65], 11, v[4:5]
	v_add_co_u32_e32 v2, vcc, 0x60000, v2
	v_lshl_add_u64 v[4:5], v[132:133], 0, v[64:65]
	s_nop 0
	v_addc_co_u32_e32 v3, vcc, 0, v3, vcc
	global_load_dwordx4 v[38:41], v[6:7], off
	global_load_dwordx4 v[42:45], v[2:3], off
	v_add_co_u32_e32 v2, vcc, s12, v4
	s_waitcnt vmcnt(63) expcnt(7) lgkmcnt(15)
	s_nop 0
	v_addc_co_u32_e32 v3, vcc, 0, v5, vcc
	s_barrier
	global_load_dwordx4 v[46:49], v[4:5], off
	global_load_dwordx4 v[50:53], v[2:3], off
	v_add_co_u32_e32 v2, vcc, s13, v4
	s_mov_b32 s37, 0
	s_nop 0
	v_addc_co_u32_e32 v3, vcc, 0, v5, vcc
	v_add_co_u32_e32 v4, vcc, s14, v4
	s_mov_b64 s[8:9], 0
	s_nop 0
	v_addc_co_u32_e32 v5, vcc, 0, v5, vcc
	global_load_dwordx4 v[54:57], v[2:3], off
	global_load_dwordx4 v[58:61], v[4:5], off
	v_mov_b32_e32 v2, 0
	v_mov_b32_e32 v3, v2
	v_mov_b32_e32 v4, v2
	v_mov_b32_e32 v5, v2
	v_mov_b32_e32 v6, v2
	v_mov_b32_e32 v7, v2
	v_mov_b32_e32 v8, v2
	v_mov_b32_e32 v9, v2
	v_mov_b32_e32 v10, v2
	v_mov_b32_e32 v11, v2
	v_mov_b32_e32 v12, v2
	v_mov_b32_e32 v13, v2
	v_mov_b32_e32 v14, v2
	v_mov_b32_e32 v15, v2
	v_mov_b32_e32 v16, v2
	v_mov_b32_e32 v17, v2
	v_mov_b32_e32 v18, v2
	v_mov_b32_e32 v19, v2
	v_mov_b32_e32 v20, v2
	v_mov_b32_e32 v21, v2
	v_mov_b32_e32 v22, v2
	v_mov_b32_e32 v23, v2
	v_mov_b32_e32 v24, v2
	v_mov_b32_e32 v25, v2
	v_mov_b32_e32 v26, v2
	v_mov_b32_e32 v27, v2
	v_mov_b32_e32 v28, v2
	v_lshl_add_u64 v[136:137], v[134:135], 0, v[62:63]
	v_lshl_add_u64 v[138:139], v[134:135], 0, v[64:65]
	v_mov_b32_e32 v29, v2
	v_mov_b32_e32 v62, v2
	v_mov_b32_e32 v63, v2
	v_mov_b32_e32 v64, v2
	v_mov_b32_e32 v65, v2
	v_mov_b32_e32 v66, v2
	v_mov_b32_e32 v67, v2
	v_mov_b32_e32 v68, v2
	v_mov_b32_e32 v69, v2
	v_mov_b32_e32 v70, v2
	v_mov_b32_e32 v71, v2
	v_mov_b32_e32 v72, v2
	v_mov_b32_e32 v73, v2
	v_mov_b32_e32 v74, v2
	v_mov_b32_e32 v75, v2
	v_mov_b32_e32 v76, v2
	v_mov_b32_e32 v77, v2
	v_mov_b32_e32 v78, v2
	v_mov_b32_e32 v79, v2
	v_mov_b32_e32 v80, v2
	v_mov_b32_e32 v81, v2
	v_mov_b32_e32 v82, v2
	v_mov_b32_e32 v83, v2
	v_mov_b32_e32 v84, v2
	s_waitcnt vmcnt(7)
	ds_write_b128 v146, v[30:33]
	s_waitcnt vmcnt(6)
	ds_write_b128 v146, v[34:37] offset:8192
	s_waitcnt vmcnt(5)
	ds_write_b128 v146, v[38:41] offset:16384
	s_waitcnt vmcnt(4)
	ds_write_b128 v146, v[42:45] offset:24576
	s_waitcnt vmcnt(3)
	ds_write_b128 v147, v[46:49]
	s_waitcnt vmcnt(2)
	ds_write_b128 v147, v[50:53] offset:8192
	s_waitcnt vmcnt(1)
	ds_write_b128 v147, v[54:57] offset:16384
	s_waitcnt vmcnt(0)
	ds_write_b128 v147, v[58:61] offset:24576
	v_mov_b32_e32 v30, v2
	v_mov_b32_e32 v31, v2
	v_mov_b32_e32 v32, v2
	v_mov_b32_e32 v33, v2
	v_mov_b32_e32 v34, v2
	v_mov_b32_e32 v35, v2
	v_mov_b32_e32 v36, v2
	v_mov_b32_e32 v37, v2
	v_mov_b32_e32 v38, v2
	v_mov_b32_e32 v39, v2
	v_mov_b32_e32 v40, v2
	v_mov_b32_e32 v41, v2
	v_mov_b32_e32 v42, v2
	v_mov_b32_e32 v43, v2
	v_mov_b32_e32 v44, v2
	v_mov_b32_e32 v45, v2
	v_mov_b32_e32 v46, v2
	v_mov_b32_e32 v47, v2
	v_mov_b32_e32 v48, v2
	v_mov_b32_e32 v49, v2
	v_mov_b32_e32 v50, v2
	v_mov_b32_e32 v51, v2
	v_mov_b32_e32 v52, v2
	v_mov_b32_e32 v53, v2
	v_mov_b32_e32 v54, v2
	v_mov_b32_e32 v55, v2
	v_mov_b32_e32 v56, v2
	v_mov_b32_e32 v57, v2
	v_mov_b32_e32 v58, v2
	v_mov_b32_e32 v59, v2
	v_mov_b32_e32 v60, v2
	v_mov_b32_e32 v61, v2
	v_mov_b32_e32 v85, v2
	v_mov_b32_e32 v86, v2
	v_mov_b32_e32 v87, v2
	v_mov_b32_e32 v88, v2
	v_mov_b32_e32 v89, v2
	v_mov_b32_e32 v90, v2
	v_mov_b32_e32 v91, v2
	v_mov_b32_e32 v92, v2
	v_mov_b32_e32 v93, v2
	v_mov_b32_e32 v94, v2
	v_mov_b32_e32 v95, v2
	v_mov_b32_e32 v96, v2
	v_mov_b32_e32 v97, v2
	v_mov_b32_e32 v98, v2
	v_mov_b32_e32 v99, v2
	v_mov_b32_e32 v100, v2
	v_mov_b32_e32 v101, v2
	v_mov_b32_e32 v102, v2
	v_mov_b32_e32 v103, v2
	v_mov_b32_e32 v104, v2
	v_mov_b32_e32 v105, v2
	v_mov_b32_e32 v106, v2
	v_mov_b32_e32 v107, v2
	v_mov_b32_e32 v108, v2
	v_mov_b32_e32 v109, v2
	v_mov_b32_e32 v110, v2
	v_mov_b32_e32 v111, v2
	v_mov_b32_e32 v112, v2
	v_mov_b32_e32 v113, v2
	v_mov_b32_e32 v114, v2
	v_mov_b32_e32 v115, v2
	v_mov_b32_e32 v116, v2
	v_mov_b32_e32 v117, v2
	v_mov_b32_e32 v118, v2
	v_mov_b32_e32 v119, v2
	v_mov_b32_e32 v120, v2
	v_mov_b32_e32 v121, v2
	v_mov_b32_e32 v122, v2
	v_mov_b32_e32 v123, v2
	v_mov_b32_e32 v124, v2
	v_mov_b32_e32 v125, v2
	v_mov_b32_e32 v126, v2
	v_mov_b32_e32 v127, v2
	v_mov_b32_e32 v128, v2
	v_mov_b32_e32 v129, v2
	s_waitcnt lgkmcnt(0)
	s_barrier
	s_movk_i32 s97, 0x70
	v_readfirstlane_b32 s98, v136
	v_readfirstlane_b32 s99, v137
	v_subrev_u32_e32 v248, s98, v136
	v_bfi_b32 v248, s97, v146, v248
	v_add_u32_e32 v140, s15, v248
	v_add_u32_e32 v152, s16, v248
	v_add_u32_e32 v156, s17, v248
	v_add_u32_e32 v160, s18, v248
	s_add_u32 s98, s98, s8
	s_addc_u32 s99, s99, s9
	s_add_u32 s98, s98, 0x80
	s_addc_u32 s99, s99, 0
	v_readfirstlane_b32 s100, v138
	v_readfirstlane_b32 s101, v139
	v_subrev_u32_e32 v250, s100, v138
	v_bfi_b32 v250, s97, v146, v250
	v_add_u32_e32 v164, s19, v250
	v_add_u32_e32 v168, s20, v250
	v_add_u32_e32 v172, s21, v250
	v_add_u32_e32 v176, s22, v250
	s_add_u32 s100, s100, s8
	s_addc_u32 s101, s101, s9
	s_add_u32 s100, s100, 0x80
	s_addc_u32 s101, s101, 0
	v_readfirstlane_b32 s96, v146
	s_and_b32 s96, s96, 0xfc00
	s_xor_b32 s96, s96, 0x8000
	s_mov_b32 m0, s96
	s_nop 0
	global_load_lds_dwordx4 v140, s[98:99]
	s_add_u32 m0, m0, 0x2000
	s_nop 0
	global_load_lds_dwordx4 v152, s[98:99]
	s_add_u32 m0, m0, 0x2000
	s_nop 0
	global_load_lds_dwordx4 v156, s[98:99]
	s_add_u32 m0, m0, 0x2000
	s_nop 0
	global_load_lds_dwordx4 v160, s[98:99]
	s_add_u32 m0, m0, 0xa000
	s_nop 0
	global_load_lds_dwordx4 v164, s[100:101]
	s_add_u32 m0, m0, 0x2000
	s_nop 0
	global_load_lds_dwordx4 v168, s[100:101]
	s_add_u32 m0, m0, 0x2000
	s_nop 0
	global_load_lds_dwordx4 v172, s[100:101]
	s_add_u32 m0, m0, 0x2000
	s_nop 0
	global_load_lds_dwordx4 v176, s[100:101]
	v_mov_b32_e32 v223, v148
	v_mov_b32_e32 v249, v149
	ds_read_b128 v[180:183], v223
	ds_read_b128 v[184:187], v223 offset:2048
	ds_read_b128 v[188:191], v223 offset:4096
	ds_read_b128 v[192:195], v223 offset:6144
	ds_read_b128 v[212:215], v249
	ds_read_b128 v[218:221], v249 offset:2048
	ds_read_b128 v[224:227], v249 offset:4096
	ds_read_b128 v[228:231], v249 offset:6144

.LBB0_749:
	s_mul_hi_i32 s0, s3, 0x2e8ba2e9
	s_lshr_b32 s1, s0, 31
	s_ashr_i32 s0, s0, 4
	s_add_i32 s24, s0, s1
	s_mul_i32 s1, s24, 0xffffffa8
	s_add_i32 s1, s1, s3
	s_ashr_i32 s21, s1, 31
	s_lshl_b32 s0, s24, 2
	s_lshr_b32 s21, s21, 30
	s_add_i32 s21, s1, s21
	s_add_i32 s0, s6, s0
	s_ashr_i32 s22, s21, 2
	s_add_i32 s0, s0, s1
	s_lshl_b32 s25, s22, 10
	s_lshl_b32 s0, s0, 8
	s_sub_i32 s21, s0, s25
	v_or_b32_e32 v2, s21, v1
	v_ashrrev_i32_e32 v3, 31, v2
	v_lshlrev_b64 v[2:3], 11, v[2:3]
	v_lshl_add_u64 v[2:3], v[132:133], 0, v[2:3]
	v_add_co_u32_e32 v6, vcc, s9, v2
	s_lshl_b32 s22, s22, 8
	s_nop 0
	v_addc_co_u32_e32 v7, vcc, 0, v3, vcc
	v_or_b32_e32 v4, s22, v1
	global_load_dwordx4 v[20:23], v[2:3], off
	global_load_dwordx4 v[24:27], v[6:7], off
	v_add_co_u32_e32 v6, vcc, s10, v2
	v_ashrrev_i32_e32 v5, 31, v4
	s_nop 0
	v_addc_co_u32_e32 v7, vcc, 0, v3, vcc
	v_lshlrev_b64 v[52:53], 11, v[4:5]
	v_add_co_u32_e32 v2, vcc, s11, v2
	v_lshl_add_u64 v[4:5], v[134:135], 0, v[52:53]
	s_nop 0
	v_addc_co_u32_e32 v3, vcc, 0, v3, vcc
	global_load_dwordx4 v[28:31], v[6:7], off
	global_load_dwordx4 v[32:35], v[2:3], off
	v_add_co_u32_e32 v2, vcc, s9, v4
	s_waitcnt vmcnt(63) expcnt(7) lgkmcnt(15)
	s_nop 0
	v_addc_co_u32_e32 v3, vcc, 0, v5, vcc
	s_barrier
	global_load_dwordx4 v[36:39], v[4:5], off
	global_load_dwordx4 v[40:43], v[2:3], off
	v_add_co_u32_e32 v2, vcc, s10, v4
	s_mulk_i32 s24, 0x5400
	s_nop 0
	v_addc_co_u32_e32 v3, vcc, 0, v5, vcc
	v_add_co_u32_e32 v4, vcc, s11, v4
	v_subrev_u32_e32 v19, s25, v130
	s_nop 0
	v_addc_co_u32_e32 v5, vcc, 0, v5, vcc
	global_load_dwordx4 v[44:47], v[2:3], off
	global_load_dwordx4 v[48:51], v[4:5], off
	v_subrev_u32_e32 v54, s24, v19
	v_ashrrev_i32_e32 v55, 31, v54
	v_lshlrev_b64 v[54:55], 11, v[54:55]
	s_mov_b64 s[0:1], 0
	s_mov_b32 s23, 0
	v_mov_b32_e32 v2, 0
	v_mov_b32_e32 v3, v131
	v_mov_b32_e32 v4, v131
	v_mov_b32_e32 v5, v131
	v_mov_b32_e32 v6, 0
	v_mov_b32_e32 v7, v131
	v_mov_b32_e32 v8, v131
	v_mov_b32_e32 v9, v131
	v_mov_b32_e32 v10, 0
	v_mov_b32_e32 v11, v131
	v_mov_b32_e32 v12, v131
	v_mov_b32_e32 v13, v131
	v_mov_b32_e32 v14, 0
	v_mov_b32_e32 v15, v131
	v_mov_b32_e32 v16, v131
	v_mov_b32_e32 v17, v131
	v_mov_b32_e32 v18, 0
	v_lshl_add_u64 v[140:141], v[138:139], 0, v[52:53]
	v_lshl_add_u64 v[142:143], v[138:139], 0, v[54:55]
	v_mov_b32_e32 v19, v131
	v_mov_b32_e32 v52, v131
	v_mov_b32_e32 v53, v131
	v_mov_b32_e32 v54, 0
	v_mov_b32_e32 v55, v131
	v_mov_b32_e32 v56, v131
	v_mov_b32_e32 v57, v131
	v_mov_b32_e32 v58, 0
	v_mov_b32_e32 v59, v131
	v_mov_b32_e32 v60, v131
	v_mov_b32_e32 v61, v131
	v_mov_b32_e32 v62, 0
	v_mov_b32_e32 v63, v131
	v_mov_b32_e32 v64, v131
	v_mov_b32_e32 v65, v131
	v_mov_b32_e32 v66, 0
	v_mov_b32_e32 v67, v131
	v_mov_b32_e32 v68, v131
	v_mov_b32_e32 v69, v131
	v_mov_b32_e32 v70, 0
	v_mov_b32_e32 v71, v131
	v_mov_b32_e32 v72, v131
	v_mov_b32_e32 v73, v131
	v_mov_b32_e32 v74, 0
	s_waitcnt vmcnt(7)
	ds_write_b128 v144, v[20:23]
	s_waitcnt vmcnt(6)
	ds_write_b128 v144, v[24:27] offset:8192
	s_waitcnt vmcnt(5)
	ds_write_b128 v144, v[28:31] offset:16384
	s_waitcnt vmcnt(4)
	ds_write_b128 v144, v[32:35] offset:24576
	s_waitcnt vmcnt(3)
	ds_write_b128 v145, v[36:39]
	s_waitcnt vmcnt(2)
	ds_write_b128 v145, v[40:43] offset:8192
	s_waitcnt vmcnt(1)
	ds_write_b128 v145, v[44:47] offset:16384
	s_waitcnt vmcnt(0)
	ds_write_b128 v145, v[48:51] offset:24576
	v_mov_b32_e32 v20, v131
	v_mov_b32_e32 v21, v131
	v_mov_b32_e32 v22, 0
	v_mov_b32_e32 v23, v131
	v_mov_b32_e32 v24, v131
	v_mov_b32_e32 v25, v131
	v_mov_b32_e32 v26, 0
	v_mov_b32_e32 v27, v131
	v_mov_b32_e32 v28, v131
	v_mov_b32_e32 v29, v131
	v_mov_b32_e32 v30, 0
	v_mov_b32_e32 v31, v131
	v_mov_b32_e32 v32, v131
	v_mov_b32_e32 v33, v131
	v_mov_b32_e32 v34, 0
	v_mov_b32_e32 v35, v131
	v_mov_b32_e32 v36, v131
	v_mov_b32_e32 v37, v131
	v_mov_b32_e32 v38, 0
	v_mov_b32_e32 v39, v131
	v_mov_b32_e32 v40, v131
	v_mov_b32_e32 v41, v131
	v_mov_b32_e32 v42, 0
	v_mov_b32_e32 v43, v131
	v_mov_b32_e32 v44, v131
	v_mov_b32_e32 v45, v131
	v_mov_b32_e32 v46, 0
	v_mov_b32_e32 v47, v131
	v_mov_b32_e32 v48, v131
	v_mov_b32_e32 v49, v131
	v_mov_b32_e32 v50, 0
	v_mov_b32_e32 v51, v131
	v_mov_b32_e32 v75, v131
	v_mov_b32_e32 v76, v131
	v_mov_b32_e32 v77, v131
	v_mov_b32_e32 v78, 0
	v_mov_b32_e32 v79, v131
	v_mov_b32_e32 v80, v131
	v_mov_b32_e32 v81, v131
	v_mov_b32_e32 v82, 0
	v_mov_b32_e32 v83, v131
	v_mov_b32_e32 v84, v131
	v_mov_b32_e32 v85, v131
	v_mov_b32_e32 v86, 0
	v_mov_b32_e32 v87, v131
	v_mov_b32_e32 v88, v131
	v_mov_b32_e32 v89, v131
	v_mov_b32_e32 v90, 0
	v_mov_b32_e32 v91, v131
	v_mov_b32_e32 v92, v131
	v_mov_b32_e32 v93, v131
	v_mov_b32_e32 v94, 0
	v_mov_b32_e32 v95, v131
	v_mov_b32_e32 v96, v131
	v_mov_b32_e32 v97, v131
	v_mov_b32_e32 v98, 0
	v_mov_b32_e32 v99, v131
	v_mov_b32_e32 v100, v131
	v_mov_b32_e32 v101, v131
	v_mov_b32_e32 v102, 0
	v_mov_b32_e32 v103, v131
	v_mov_b32_e32 v104, v131
	v_mov_b32_e32 v105, v131
	v_mov_b32_e32 v106, 0
	v_mov_b32_e32 v107, v131
	v_mov_b32_e32 v108, v131
	v_mov_b32_e32 v109, v131
	v_mov_b32_e32 v110, 0
	v_mov_b32_e32 v111, v131
	v_mov_b32_e32 v112, v131
	v_mov_b32_e32 v113, v131
	v_mov_b32_e32 v114, 0
	v_mov_b32_e32 v115, v131
	v_mov_b32_e32 v116, v131
	v_mov_b32_e32 v117, v131
	v_mov_b32_e32 v118, 0
	v_mov_b32_e32 v119, v131
	v_mov_b32_e32 v120, v131
	v_mov_b32_e32 v121, v131
	v_mov_b32_e32 v122, 0
	v_mov_b32_e32 v123, v131
	v_mov_b32_e32 v124, v131
	v_mov_b32_e32 v125, v131
	v_mov_b32_e32 v126, 0
	v_mov_b32_e32 v127, v131
	v_mov_b32_e32 v128, v131
	v_mov_b32_e32 v129, v131
	s_waitcnt lgkmcnt(0)
	s_barrier
	s_movk_i32 s97, 0x70
	v_readfirstlane_b32 s98, v142
	v_readfirstlane_b32 s99, v143
	v_subrev_u32_e32 v215, s98, v142
	v_bfi_b32 v215, s97, v144, v215
	v_add_u32_e32 v150, s12, v215
	v_add_u32_e32 v154, s13, v215
	v_add_u32_e32 v158, s14, v215
	v_add_u32_e32 v162, s15, v215
	s_add_u32 s98, s98, s0
	s_addc_u32 s99, s99, s1
	s_add_u32 s98, s98, 0x80
	s_addc_u32 s99, s99, 0
	v_readfirstlane_b32 s100, v140
	v_readfirstlane_b32 s101, v141
	v_subrev_u32_e32 v252, s100, v140
	v_bfi_b32 v252, s97, v144, v252
	v_add_u32_e32 v166, s16, v252
	v_add_u32_e32 v170, s17, v252
	v_add_u32_e32 v174, s18, v252
	v_add_u32_e32 v178, s19, v252
	s_add_u32 s100, s100, s0
	s_addc_u32 s101, s101, s1
	s_add_u32 s100, s100, 0x80
	s_addc_u32 s101, s101, 0
	v_readfirstlane_b32 s96, v144
	s_and_b32 s96, s96, 0xfc00
	s_xor_b32 s96, s96, 0x8000
	s_mov_b32 m0, s96
	s_nop 0
	global_load_lds_dwordx4 v150, s[98:99]
	s_add_u32 m0, m0, 0x2000
	s_nop 0
	global_load_lds_dwordx4 v154, s[98:99]
	s_add_u32 m0, m0, 0x2000
	s_nop 0
	global_load_lds_dwordx4 v158, s[98:99]
	s_add_u32 m0, m0, 0x2000
	s_nop 0
	global_load_lds_dwordx4 v162, s[98:99]
	s_add_u32 m0, m0, 0xa000
	s_nop 0
	global_load_lds_dwordx4 v166, s[100:101]
	s_add_u32 m0, m0, 0x2000
	s_nop 0
	global_load_lds_dwordx4 v170, s[100:101]
	s_add_u32 m0, m0, 0x2000
	s_nop 0
	global_load_lds_dwordx4 v174, s[100:101]
	s_add_u32 m0, m0, 0x2000
	s_nop 0
	global_load_lds_dwordx4 v178, s[100:101]
	v_mov_b32_e32 v214, v146
	v_mov_b32_e32 v223, v147
	ds_read_b128 v[182:185], v214
	ds_read_b128 v[186:189], v214 offset:2048
	ds_read_b128 v[190:193], v214 offset:4096
	ds_read_b128 v[194:197], v214 offset:6144
	ds_read_b128 v[218:221], v223
	ds_read_b128 v[224:227], v223 offset:2048
	ds_read_b128 v[228:231], v223 offset:4096
	ds_read_b128 v[232:235], v223 offset:6144

.LBB0_773:
	s_lshl_b32 s37, s29, 8
	v_or_b32_e32 v27, s37, v1
	v_mad_i64_i32 v[2:3], s[8:9], v27, s12, v[130:131]
	v_add_co_u32_e32 v6, vcc, 0x58000, v2
	s_lshl_b32 s36, s28, 8
	s_nop 0
	v_addc_co_u32_e32 v7, vcc, 0, v3, vcc
	global_load_dwordx4 v[28:31], v[2:3], off
	global_load_dwordx4 v[32:35], v[6:7], off
	v_add_co_u32_e32 v6, vcc, 0xb0000, v2
	v_or_b32_e32 v60, s36, v1
	s_nop 0
	v_addc_co_u32_e32 v7, vcc, 0, v3, vcc
	v_add_co_u32_e32 v2, vcc, 0x108000, v2
	v_mad_i64_i32 v[4:5], s[8:9], v60, s12, v[132:133]
	s_nop 0
	v_addc_co_u32_e32 v3, vcc, 0, v3, vcc
	global_load_dwordx4 v[36:39], v[6:7], off
	global_load_dwordx4 v[40:43], v[2:3], off
	v_add_co_u32_e32 v2, vcc, s13, v4
	s_waitcnt vmcnt(63) expcnt(7) lgkmcnt(15)
	s_nop 0
	v_addc_co_u32_e32 v3, vcc, 0, v5, vcc
	s_barrier
	global_load_dwordx4 v[44:47], v[4:5], off
	global_load_dwordx4 v[48:51], v[2:3], off
	v_add_co_u32_e32 v2, vcc, s14, v4
	s_mov_b32 s38, 0
	s_nop 0
	v_addc_co_u32_e32 v3, vcc, 0, v5, vcc
	v_add_co_u32_e32 v4, vcc, s15, v4
	s_mov_b64 s[8:9], 0
	s_nop 0
	v_addc_co_u32_e32 v5, vcc, 0, v5, vcc
	global_load_dwordx4 v[52:55], v[2:3], off
	global_load_dwordx4 v[56:59], v[4:5], off
	v_mov_b32_e32 v2, 0
	v_mov_b32_e32 v3, v2
	v_mov_b32_e32 v4, v2
	v_mov_b32_e32 v5, v2
	v_mov_b32_e32 v6, v2
	v_mov_b32_e32 v7, v2
	v_mov_b32_e32 v8, v2
	v_mov_b32_e32 v9, v2
	v_mov_b32_e32 v10, v2
	v_mov_b32_e32 v11, v2
	v_mov_b32_e32 v12, v2
	v_mov_b32_e32 v13, v2
	v_mov_b32_e32 v14, v2
	v_mov_b32_e32 v15, v2
	v_mov_b32_e32 v16, v2
	v_mov_b32_e32 v17, v2
	v_mov_b32_e32 v18, v2
	v_mov_b32_e32 v19, v2
	v_mov_b32_e32 v20, v2
	v_mov_b32_e32 v21, v2
	v_mov_b32_e32 v22, v2
	v_mov_b32_e32 v23, v2
	v_mov_b32_e32 v24, v2
	v_mov_b32_e32 v25, v2
	v_mov_b32_e32 v26, v2
	v_mad_i64_i32 v[136:137], s[40:41], v27, s12, v[134:135]
	v_mad_i64_i32 v[138:139], s[40:41], v60, s12, v[134:135]
	v_mov_b32_e32 v27, v2
	v_mov_b32_e32 v60, v2
	v_mov_b32_e32 v61, v2
	v_mov_b32_e32 v62, v2
	v_mov_b32_e32 v63, v2
	v_mov_b32_e32 v64, v2
	v_mov_b32_e32 v65, v2
	v_mov_b32_e32 v66, v2
	v_mov_b32_e32 v67, v2
	v_mov_b32_e32 v68, v2
	v_mov_b32_e32 v69, v2
	v_mov_b32_e32 v70, v2
	v_mov_b32_e32 v71, v2
	v_mov_b32_e32 v72, v2
	v_mov_b32_e32 v73, v2
	v_mov_b32_e32 v74, v2
	v_mov_b32_e32 v75, v2
	v_mov_b32_e32 v76, v2
	v_mov_b32_e32 v77, v2
	v_mov_b32_e32 v78, v2
	v_mov_b32_e32 v79, v2
	v_mov_b32_e32 v80, v2
	v_mov_b32_e32 v81, v2
	v_mov_b32_e32 v82, v2
	s_waitcnt vmcnt(7)
	ds_write_b128 v146, v[28:31]
	s_waitcnt vmcnt(6)
	ds_write_b128 v146, v[32:35] offset:8192
	s_waitcnt vmcnt(5)
	ds_write_b128 v146, v[36:39] offset:16384
	s_waitcnt vmcnt(4)
	ds_write_b128 v146, v[40:43] offset:24576
	s_waitcnt vmcnt(3)
	ds_write_b128 v147, v[44:47]
	s_waitcnt vmcnt(2)
	ds_write_b128 v147, v[48:51] offset:8192
	s_waitcnt vmcnt(1)
	ds_write_b128 v147, v[52:55] offset:16384
	s_waitcnt vmcnt(0)
	ds_write_b128 v147, v[56:59] offset:24576
	v_mov_b32_e32 v28, v2
	v_mov_b32_e32 v29, v2
	v_mov_b32_e32 v30, v2
	v_mov_b32_e32 v31, v2
	v_mov_b32_e32 v32, v2
	v_mov_b32_e32 v33, v2
	v_mov_b32_e32 v34, v2
	v_mov_b32_e32 v35, v2
	v_mov_b32_e32 v36, v2
	v_mov_b32_e32 v37, v2
	v_mov_b32_e32 v38, v2
	v_mov_b32_e32 v39, v2
	v_mov_b32_e32 v40, v2
	v_mov_b32_e32 v41, v2
	v_mov_b32_e32 v42, v2
	v_mov_b32_e32 v43, v2
	v_mov_b32_e32 v44, v2
	v_mov_b32_e32 v45, v2
	v_mov_b32_e32 v46, v2
	v_mov_b32_e32 v47, v2
	v_mov_b32_e32 v48, v2
	v_mov_b32_e32 v49, v2
	v_mov_b32_e32 v50, v2
	v_mov_b32_e32 v51, v2
	v_mov_b32_e32 v52, v2
	v_mov_b32_e32 v53, v2
	v_mov_b32_e32 v54, v2
	v_mov_b32_e32 v55, v2
	v_mov_b32_e32 v56, v2
	v_mov_b32_e32 v57, v2
	v_mov_b32_e32 v58, v2
	v_mov_b32_e32 v59, v2
	v_mov_b32_e32 v83, v2
	v_mov_b32_e32 v84, v2
	v_mov_b32_e32 v85, v2
	v_mov_b32_e32 v86, v2
	v_mov_b32_e32 v87, v2
	v_mov_b32_e32 v88, v2
	v_mov_b32_e32 v89, v2
	v_mov_b32_e32 v90, v2
	v_mov_b32_e32 v91, v2
	v_mov_b32_e32 v92, v2
	v_mov_b32_e32 v93, v2
	v_mov_b32_e32 v94, v2
	v_mov_b32_e32 v95, v2
	v_mov_b32_e32 v96, v2
	v_mov_b32_e32 v97, v2
	v_mov_b32_e32 v98, v2
	v_mov_b32_e32 v99, v2
	v_mov_b32_e32 v100, v2
	v_mov_b32_e32 v101, v2
	v_mov_b32_e32 v102, v2
	v_mov_b32_e32 v103, v2
	v_mov_b32_e32 v104, v2
	v_mov_b32_e32 v105, v2
	v_mov_b32_e32 v106, v2
	v_mov_b32_e32 v107, v2
	v_mov_b32_e32 v108, v2
	v_mov_b32_e32 v109, v2
	v_mov_b32_e32 v110, v2
	v_mov_b32_e32 v111, v2
	v_mov_b32_e32 v112, v2
	v_mov_b32_e32 v113, v2
	v_mov_b32_e32 v114, v2
	v_mov_b32_e32 v115, v2
	v_mov_b32_e32 v116, v2
	v_mov_b32_e32 v117, v2
	v_mov_b32_e32 v118, v2
	v_mov_b32_e32 v119, v2
	v_mov_b32_e32 v120, v2
	v_mov_b32_e32 v121, v2
	v_mov_b32_e32 v122, v2
	v_mov_b32_e32 v123, v2
	v_mov_b32_e32 v124, v2
	v_mov_b32_e32 v125, v2
	v_mov_b32_e32 v126, v2
	v_mov_b32_e32 v127, v2
	v_mov_b32_e32 v128, v2
	v_mov_b32_e32 v129, v2
	s_waitcnt lgkmcnt(0)
	s_barrier
	s_movk_i32 s97, 0x70
	v_readfirstlane_b32 s98, v136
	v_readfirstlane_b32 s99, v137
	v_subrev_u32_e32 v248, s98, v136
	v_bfi_b32 v248, s97, v146, v248
	v_add_u32_e32 v140, s16, v248
	v_add_u32_e32 v152, s17, v248
	v_add_u32_e32 v156, s18, v248
	v_add_u32_e32 v160, s19, v248
	s_add_u32 s98, s98, s8
	s_addc_u32 s99, s99, s9
	s_add_u32 s98, s98, 0x80
	s_addc_u32 s99, s99, 0
	v_readfirstlane_b32 s100, v138
	v_readfirstlane_b32 s101, v139
	v_subrev_u32_e32 v250, s100, v138
	v_bfi_b32 v250, s97, v146, v250
	v_add_u32_e32 v164, s20, v250
	v_add_u32_e32 v168, s21, v250
	v_add_u32_e32 v172, s22, v250
	v_add_u32_e32 v176, s23, v250
	s_add_u32 s100, s100, s8
	s_addc_u32 s101, s101, s9
	s_add_u32 s100, s100, 0x80
	s_addc_u32 s101, s101, 0
	v_readfirstlane_b32 s96, v146
	s_and_b32 s96, s96, 0xfc00
	s_xor_b32 s96, s96, 0x8000
	s_mov_b32 m0, s96
	s_nop 0
	global_load_lds_dwordx4 v140, s[98:99]
	s_add_u32 m0, m0, 0x2000
	s_nop 0
	global_load_lds_dwordx4 v152, s[98:99]
	s_add_u32 m0, m0, 0x2000
	s_nop 0
	global_load_lds_dwordx4 v156, s[98:99]
	s_add_u32 m0, m0, 0x2000
	s_nop 0
	global_load_lds_dwordx4 v160, s[98:99]
	s_add_u32 m0, m0, 0xa000
	s_nop 0
	global_load_lds_dwordx4 v164, s[100:101]
	s_add_u32 m0, m0, 0x2000
	s_nop 0
	global_load_lds_dwordx4 v168, s[100:101]
	s_add_u32 m0, m0, 0x2000
	s_nop 0
	global_load_lds_dwordx4 v172, s[100:101]
	s_add_u32 m0, m0, 0x2000
	s_nop 0
	global_load_lds_dwordx4 v176, s[100:101]
	v_mov_b32_e32 v223, v148
	v_mov_b32_e32 v249, v149
	ds_read_b128 v[180:183], v223
	ds_read_b128 v[184:187], v223 offset:2048
	ds_read_b128 v[188:191], v223 offset:4096
	ds_read_b128 v[192:195], v223 offset:6144
	ds_read_b128 v[212:215], v249
	ds_read_b128 v[218:221], v249 offset:2048
	ds_read_b128 v[224:227], v249 offset:4096
	ds_read_b128 v[228:231], v249 offset:6144
